# GEMM K-loops: removed the redundant mid-block s_setprio 0/1 pair inside each 32-MFMA block (on top of the LRU parameter-load hoist)
# baseline (speedup 1.0000x reference)
; #define PG8_STAGE(bufoff, gbase, voff) do { _Pragma("unroll") for (int _i = 0; _i < 2; ++_i) \
;         __builtin_amdgcn_global_load_lds((const unsigned*)((const char*)(gbase) + (voff)[_i]), (LAS unsigned*)(lds + (bufoff) + ldsw + _i * 8192), 16, 0, 0); } while (0)
; #define PG8_LDA(dst, b, h) do { _Pragma("unroll") for (int m = 0; m < 4; ++m) _Pragma("unroll") for (int k = 0; k < 2; ++k) dst[m][k] = *(const LAS bf16x8*)(lds + PG8_SA(b, h) + aoff + m * 2048 + k * 1024); } while (0)
; #define PG8_LDB(dst, b, h) do { _Pragma("unroll") for (int n = 0; n < 2; ++n) _Pragma("unroll") for (int k = 0; k < 2; ++k) dst[n][k] = *(const LAS bf16x8*)(lds + PG8_SB(b, h) + boff + n * 2048 + k * 1024); } while (0)
; #define PG8_MMA(ai, bj, At, Bt) do { __builtin_amdgcn_s_setprio(1); _Pragma("unroll") for (int m = 0; m < 4; ++m) _Pragma("unroll") for (int n = 0; n < 2; ++n) _Pragma("unroll") for (int k = 0; k < 2; ++k) \
;         acc[ai][bj][m][n] = __builtin_amdgcn_mfma_f32_16x16x32_bf16(Bt[n][k], At[m][k], acc[ai][bj][m][n], 0, 0, 0); __builtin_amdgcn_s_setprio(0); } while (0)
; #define PG8_WAIT_V(n) asm volatile("s_waitcnt vmcnt(" #n ")" ::: "memory")
; #define PG8_WAIT_L(n) asm volatile("s_waitcnt lgkmcnt(" #n ")" ::: "memory")
; #define PG8_BAR __builtin_amdgcn_s_barrier()
; #define PG8_SCHED __builtin_amdgcn_sched_barrier(0)
; template <class Epi, class Sched>
; __device__ __forceinline__ void gemm_phase(LAS unsigned char* lds, const int K, const Sched& S, const Epi& E) {
;     ...
;             const bool last = (t == nt - 2);
;             const char* a1 = cA + (size_t)(t + 1) * kstep;
;             const char* a2 = last ? nA : cA + (size_t)(t + 2) * kstep; const char* b2 = last ? nB : cB + (size_t)(t + 2) * kstep;
;             const char* a3 = a2 + kstep; const char* b3 = b2 + kstep;
;             PG8_LDB(B0, 0, 0); PG8_LDB(B1, 0, 1); PG8_SCHED; PG8_LDA(At, 0, 0); PG8_STAGE(PG8_SA(1, 1), a1 + hstep, voffA);
;             PG8_WAIT_V(8); PG8_WAIT_L(0); PG8_BAR; PG8_MMA(0, 0, At, B0); PG8_MMA(0, 1, At, B1); PG8_BAR; PG8_SCHED;
;             PG8_LDA(At, 0, 1); PG8_STAGE(PG8_SB(0, 0), b2, voffB); PG8_STAGE(PG8_SB(0, 1), b2 + hstep, voffB); PG8_STAGE(PG8_SA(0, 0), a2, voffA);
;             PG8_WAIT_V(8); PG8_WAIT_L(0); PG8_BAR; PG8_MMA(1, 0, At, B0); PG8_MMA(1, 1, At, B1); PG8_BAR; PG8_SCHED;
.LBB0_403:
	s_add_u32 s14, s8, 0xfffc0080
	s_addc_u32 s15, s9, -1
	s_add_i32 s16, 0, 0x10000
	s_cmp_eq_u32 s13, 12
	s_cselect_b32 s55, s2, s15
	s_cselect_b32 s54, s4, s14
	v_add_u32_e32 v128, s16, v149
	s_cselect_b32 s39, s5, s12
	s_cselect_b32 s38, s10, s11
	s_add_i32 s17, 0, 0x14000
	ds_read_b128 v[158:161], v128
	ds_read_b128 v[162:165], v128 offset:1024
	ds_read_b128 v[184:187], v128 offset:2048
	ds_read_b128 v[188:191], v128 offset:3072
	v_add_u32_e32 v128, s17, v149
	ds_read_b128 v[192:195], v128
	ds_read_b128 v[196:199], v128 offset:1024
	ds_read_b128 v[200:203], v128 offset:2048
	ds_read_b128 v[204:207], v128 offset:3072
	v_lshl_add_u64 v[166:167], s[8:9], 0, v[154:155]
	s_add_i32 m0, s59, 0xc000
	ds_read_b128 v[208:211], v147
	ds_read_b128 v[212:215], v147 offset:1024
	ds_read_b128 v[216:219], v147 offset:2048
	ds_read_b128 v[220:223], v147 offset:3072
	ds_read_b128 v[224:227], v147 offset:4096
	ds_read_b128 v[228:231], v147 offset:5120
	ds_read_b128 v[232:235], v147 offset:6144
	ds_read_b128 v[236:239], v147 offset:7168
	global_load_lds_dwordx4 v[166:167], off
	v_lshl_add_u64 v[166:167], s[8:9], 0, v[156:157]
	s_add_i32 m0, s59, 0xe000
	s_nop 0
	global_load_lds_dwordx4 v[166:167], off
	s_waitcnt vmcnt(8)
	s_waitcnt lgkmcnt(0)
	s_barrier
	s_setprio 1
	s_waitcnt lgkmcnt(0)
	v_mfma_f32_16x16x32_bf16 v[124:127], v[158:161], v[208:211], v[124:127]
	v_mfma_f32_16x16x32_bf16 v[120:123], v[184:187], v[208:211], v[120:123]
	v_mfma_f32_16x16x32_bf16 v[108:111], v[158:161], v[216:219], v[108:111]
	v_mfma_f32_16x16x32_bf16 v[104:107], v[184:187], v[216:219], v[104:107]
	v_mfma_f32_16x16x32_bf16 v[92:95], v[158:161], v[224:227], v[92:95]
	v_mfma_f32_16x16x32_bf16 v[88:91], v[184:187], v[224:227], v[88:91]
	v_mfma_f32_16x16x32_bf16 v[76:79], v[158:161], v[232:235], v[76:79]
	v_mfma_f32_16x16x32_bf16 v[72:75], v[184:187], v[232:235], v[72:75]
	v_mfma_f32_16x16x32_bf16 v[124:127], v[162:165], v[212:215], v[124:127]
	v_mfma_f32_16x16x32_bf16 v[120:123], v[188:191], v[212:215], v[120:123]
	v_mfma_f32_16x16x32_bf16 v[108:111], v[162:165], v[220:223], v[108:111]
	v_mfma_f32_16x16x32_bf16 v[104:107], v[188:191], v[220:223], v[104:107]
	v_mfma_f32_16x16x32_bf16 v[92:95], v[162:165], v[228:231], v[92:95]
	v_mfma_f32_16x16x32_bf16 v[88:91], v[188:191], v[228:231], v[88:91]
	v_mfma_f32_16x16x32_bf16 v[76:79], v[162:165], v[236:239], v[76:79]
	v_mfma_f32_16x16x32_bf16 v[72:75], v[188:191], v[236:239], v[72:75]
	v_mfma_f32_16x16x32_bf16 v[116:119], v[192:195], v[208:211], v[116:119]
	v_mfma_f32_16x16x32_bf16 v[112:115], v[200:203], v[208:211], v[112:115]
	v_mfma_f32_16x16x32_bf16 v[100:103], v[192:195], v[216:219], v[100:103]
	v_mfma_f32_16x16x32_bf16 v[96:99], v[200:203], v[216:219], v[96:99]
	v_mfma_f32_16x16x32_bf16 v[84:87], v[192:195], v[224:227], v[84:87]
	v_mfma_f32_16x16x32_bf16 v[80:83], v[200:203], v[224:227], v[80:83]
	v_mfma_f32_16x16x32_bf16 v[68:71], v[192:195], v[232:235], v[68:71]
	v_mfma_f32_16x16x32_bf16 v[64:67], v[200:203], v[232:235], v[64:67]
	v_mfma_f32_16x16x32_bf16 v[116:119], v[196:199], v[212:215], v[116:119]
	v_mfma_f32_16x16x32_bf16 v[112:115], v[204:207], v[212:215], v[112:115]
	v_mfma_f32_16x16x32_bf16 v[100:103], v[196:199], v[220:223], v[100:103]
	v_mfma_f32_16x16x32_bf16 v[96:99], v[204:207], v[220:223], v[96:99]
	v_mfma_f32_16x16x32_bf16 v[84:87], v[196:199], v[228:231], v[84:87]
	v_mfma_f32_16x16x32_bf16 v[80:83], v[204:207], v[228:231], v[80:83]
	v_mfma_f32_16x16x32_bf16 v[68:71], v[196:199], v[236:239], v[68:71]
	v_mfma_f32_16x16x32_bf16 v[64:67], v[204:207], v[236:239], v[64:67]
	s_setprio 0
	s_barrier
	s_add_i32 s14, s16, s58
	v_lshl_add_u64 v[166:167], s[38:39], 0, v[140:141]
	s_mov_b32 m0, s14
	ds_read_b128 v[208:211], v147 offset:16384
	ds_read_b128 v[212:215], v147 offset:17408
	ds_read_b128 v[216:219], v147 offset:18432
	ds_read_b128 v[220:223], v147 offset:19456
	ds_read_b128 v[224:227], v147 offset:20480
	ds_read_b128 v[228:231], v147 offset:21504
	ds_read_b128 v[232:235], v147 offset:22528
	ds_read_b128 v[236:239], v147 offset:23552
	global_load_lds_dwordx4 v[166:167], off
	s_add_i32 m0, s14, 0x2000
	s_add_u32 s14, s38, 0x40000
	v_lshl_add_u64 v[180:181], s[38:39], 0, v[144:145]
	s_addc_u32 s15, s39, 0
	s_add_i32 s16, s17, s58
	global_load_lds_dwordx4 v[180:181], off
	v_lshl_add_u64 v[182:183], s[14:15], 0, v[140:141]
	s_mov_b32 m0, s16
	v_lshl_add_u64 v[240:241], s[54:55], 0, v[142:143]
	global_load_lds_dwordx4 v[182:183], off
	v_lshl_add_u64 v[182:183], s[14:15], 0, v[144:145]
	s_add_i32 m0, s16, 0x2000
	s_nop 0
	global_load_lds_dwordx4 v[182:183], off
	v_lshl_add_u64 v[182:183], s[54:55], 0, v[138:139]
	s_mov_b32 m0, s59
	s_nop 0
	global_load_lds_dwordx4 v[182:183], off
	s_mov_b32 m0, s60
	s_nop 0
	global_load_lds_dwordx4 v[240:241], off
	s_waitcnt vmcnt(8)
	s_waitcnt lgkmcnt(0)
	s_barrier
; #define PG8_STAGE(bufoff, gbase, voff) do { _Pragma("unroll") for (int _i = 0; _i < 2; ++_i) \
;         __builtin_amdgcn_global_load_lds((const unsigned*)((const char*)(gbase) + (voff)[_i]), (LAS unsigned*)(lds + (bufoff) + ldsw + _i * 8192), 16, 0, 0); } while (0)
; #define PG8_LDA(dst, b, h) do { _Pragma("unroll") for (int m = 0; m < 4; ++m) _Pragma("unroll") for (int k = 0; k < 2; ++k) dst[m][k] = *(const LAS bf16x8*)(lds + PG8_SA(b, h) + aoff + m * 2048 + k * 1024); } while (0)
; #define PG8_LDB(dst, b, h) do { _Pragma("unroll") for (int n = 0; n < 2; ++n) _Pragma("unroll") for (int k = 0; k < 2; ++k) dst[n][k] = *(const LAS bf16x8*)(lds + PG8_SB(b, h) + boff + n * 2048 + k * 1024); } while (0)
; #define PG8_MMA(ai, bj, At, Bt) do { __builtin_amdgcn_s_setprio(1); _Pragma("unroll") for (int m = 0; m < 4; ++m) _Pragma("unroll") for (int n = 0; n < 2; ++n) _Pragma("unroll") for (int k = 0; k < 2; ++k) \
;         acc[ai][bj][m][n] = __builtin_amdgcn_mfma_f32_16x16x32_bf16(Bt[n][k], At[m][k], acc[ai][bj][m][n], 0, 0, 0); __builtin_amdgcn_s_setprio(0); } while (0)
; #define PG8_WAIT_V(n) asm volatile("s_waitcnt vmcnt(" #n ")" ::: "memory")
; #define PG8_WAIT_L(n) asm volatile("s_waitcnt lgkmcnt(" #n ")" ::: "memory")
; #define PG8_BAR __builtin_amdgcn_s_barrier()
; #define PG8_SCHED __builtin_amdgcn_sched_barrier(0)
; template <class Epi, class Sched>
; __device__ __forceinline__ void gemm_phase(LAS unsigned char* lds, const int K, const Sched& S, const Epi& E) {
;     ...
;             PG8_WAIT_V(8); PG8_WAIT_L(0); PG8_BAR; PG8_MMA(1, 0, At, B0); PG8_MMA(1, 1, At, B1); PG8_BAR; PG8_SCHED;
;             PG8_LDB(B0, 1, 0); PG8_LDB(B1, 1, 1); PG8_SCHED; PG8_LDA(At, 1, 0); PG8_STAGE(PG8_SA(0, 1), a2 + hstep, voffA);
;             PG8_WAIT_V(8); PG8_WAIT_L(0); PG8_BAR; PG8_MMA(0, 0, At, B0); PG8_MMA(0, 1, At, B1); PG8_BAR; PG8_SCHED;
	s_setprio 1
	s_waitcnt lgkmcnt(0)
	v_mfma_f32_16x16x32_bf16 v[60:63], v[158:161], v[208:211], v[60:63]
	v_mfma_f32_16x16x32_bf16 v[56:59], v[184:187], v[208:211], v[56:59]
	v_mfma_f32_16x16x32_bf16 v[44:47], v[158:161], v[216:219], v[44:47]
	v_mfma_f32_16x16x32_bf16 v[40:43], v[184:187], v[216:219], v[40:43]
	v_mfma_f32_16x16x32_bf16 v[28:31], v[158:161], v[224:227], v[28:31]
	v_mfma_f32_16x16x32_bf16 v[24:27], v[184:187], v[224:227], v[24:27]
	v_mfma_f32_16x16x32_bf16 v[12:15], v[158:161], v[232:235], v[12:15]
	v_mfma_f32_16x16x32_bf16 v[8:11], v[184:187], v[232:235], v[8:11]
	v_mfma_f32_16x16x32_bf16 v[60:63], v[162:165], v[212:215], v[60:63]
	v_mfma_f32_16x16x32_bf16 v[56:59], v[188:191], v[212:215], v[56:59]
	v_mfma_f32_16x16x32_bf16 v[44:47], v[162:165], v[220:223], v[44:47]
	v_mfma_f32_16x16x32_bf16 v[40:43], v[188:191], v[220:223], v[40:43]
	v_mfma_f32_16x16x32_bf16 v[28:31], v[162:165], v[228:231], v[28:31]
	v_mfma_f32_16x16x32_bf16 v[24:27], v[188:191], v[228:231], v[24:27]
	v_mfma_f32_16x16x32_bf16 v[12:15], v[162:165], v[236:239], v[12:15]
	v_mfma_f32_16x16x32_bf16 v[8:11], v[188:191], v[236:239], v[8:11]
	v_mfma_f32_16x16x32_bf16 v[52:55], v[192:195], v[208:211], v[52:55]
	v_mfma_f32_16x16x32_bf16 v[48:51], v[200:203], v[208:211], v[48:51]
	v_mfma_f32_16x16x32_bf16 v[36:39], v[192:195], v[216:219], v[36:39]
	v_mfma_f32_16x16x32_bf16 v[32:35], v[200:203], v[216:219], v[32:35]
	v_mfma_f32_16x16x32_bf16 v[20:23], v[192:195], v[224:227], v[20:23]
	v_mfma_f32_16x16x32_bf16 v[16:19], v[200:203], v[224:227], v[16:19]
	v_mfma_f32_16x16x32_bf16 v[4:7], v[192:195], v[232:235], v[4:7]
	v_mfma_f32_16x16x32_bf16 v[0:3], v[200:203], v[232:235], v[0:3]
	v_mfma_f32_16x16x32_bf16 v[52:55], v[196:199], v[212:215], v[52:55]
	v_mfma_f32_16x16x32_bf16 v[48:51], v[204:207], v[212:215], v[48:51]
	v_mfma_f32_16x16x32_bf16 v[36:39], v[196:199], v[220:223], v[36:39]
	v_mfma_f32_16x16x32_bf16 v[32:35], v[204:207], v[220:223], v[32:35]
	v_mfma_f32_16x16x32_bf16 v[20:23], v[196:199], v[228:231], v[20:23]
	v_mfma_f32_16x16x32_bf16 v[16:19], v[204:207], v[228:231], v[16:19]
	v_mfma_f32_16x16x32_bf16 v[4:7], v[196:199], v[236:239], v[4:7]
	v_mfma_f32_16x16x32_bf16 v[0:3], v[204:207], v[236:239], v[0:3]
	s_setprio 0
	s_barrier
	s_add_i32 s16, 0, 0x18000
	v_add_u32_e32 v128, s16, v149
	s_add_i32 s17, 0, 0x1c000
	ds_read_b128 v[158:161], v128
	ds_read_b128 v[162:165], v128 offset:1024
	ds_read_b128 v[184:187], v128 offset:2048
	ds_read_b128 v[188:191], v128 offset:3072
	v_add_u32_e32 v128, s17, v149
	ds_read_b128 v[192:195], v128
	ds_read_b128 v[196:199], v128 offset:1024
	ds_read_b128 v[200:203], v128 offset:2048
	ds_read_b128 v[204:207], v128 offset:3072
	s_add_u32 s14, s54, 0x40000
	s_addc_u32 s15, s55, 0
	s_mov_b32 m0, s61
	v_lshl_add_u64 v[242:243], s[14:15], 0, v[138:139]
	ds_read_b128 v[208:211], v147 offset:32768
	ds_read_b128 v[212:215], v147 offset:33792
	ds_read_b128 v[216:219], v147 offset:34816
	ds_read_b128 v[220:223], v147 offset:35840
	ds_read_b128 v[224:227], v147 offset:36864
	ds_read_b128 v[228:231], v147 offset:37888
	ds_read_b128 v[232:235], v147 offset:38912
	ds_read_b128 v[236:239], v147 offset:39936
	global_load_lds_dwordx4 v[242:243], off
	v_lshl_add_u64 v[242:243], s[14:15], 0, v[142:143]
	s_mov_b32 m0, s62
	s_nop 0
	global_load_lds_dwordx4 v[242:243], off
	s_waitcnt vmcnt(8)
	s_waitcnt lgkmcnt(0)
	s_barrier
	s_setprio 1
	s_waitcnt lgkmcnt(0)
	v_mfma_f32_16x16x32_bf16 v[124:127], v[158:161], v[208:211], v[124:127]
	v_mfma_f32_16x16x32_bf16 v[120:123], v[184:187], v[208:211], v[120:123]
	v_mfma_f32_16x16x32_bf16 v[108:111], v[158:161], v[216:219], v[108:111]
	v_mfma_f32_16x16x32_bf16 v[104:107], v[184:187], v[216:219], v[104:107]
	v_mfma_f32_16x16x32_bf16 v[92:95], v[158:161], v[224:227], v[92:95]
	v_mfma_f32_16x16x32_bf16 v[88:91], v[184:187], v[224:227], v[88:91]
	v_mfma_f32_16x16x32_bf16 v[76:79], v[158:161], v[232:235], v[76:79]
	v_mfma_f32_16x16x32_bf16 v[72:75], v[184:187], v[232:235], v[72:75]
	v_mfma_f32_16x16x32_bf16 v[124:127], v[162:165], v[212:215], v[124:127]
	v_mfma_f32_16x16x32_bf16 v[120:123], v[188:191], v[212:215], v[120:123]
	v_mfma_f32_16x16x32_bf16 v[108:111], v[162:165], v[220:223], v[108:111]
	v_mfma_f32_16x16x32_bf16 v[104:107], v[188:191], v[220:223], v[104:107]
	v_mfma_f32_16x16x32_bf16 v[92:95], v[162:165], v[228:231], v[92:95]
	v_mfma_f32_16x16x32_bf16 v[88:91], v[188:191], v[228:231], v[88:91]
	v_mfma_f32_16x16x32_bf16 v[76:79], v[162:165], v[236:239], v[76:79]
	v_mfma_f32_16x16x32_bf16 v[72:75], v[188:191], v[236:239], v[72:75]
	v_mfma_f32_16x16x32_bf16 v[116:119], v[192:195], v[208:211], v[116:119]
	v_mfma_f32_16x16x32_bf16 v[112:115], v[200:203], v[208:211], v[112:115]
	v_mfma_f32_16x16x32_bf16 v[100:103], v[192:195], v[216:219], v[100:103]
	v_mfma_f32_16x16x32_bf16 v[96:99], v[200:203], v[216:219], v[96:99]
	v_mfma_f32_16x16x32_bf16 v[84:87], v[192:195], v[224:227], v[84:87]
	v_mfma_f32_16x16x32_bf16 v[80:83], v[200:203], v[224:227], v[80:83]
	v_mfma_f32_16x16x32_bf16 v[68:71], v[192:195], v[232:235], v[68:71]
	v_mfma_f32_16x16x32_bf16 v[64:67], v[200:203], v[232:235], v[64:67]
	v_mfma_f32_16x16x32_bf16 v[116:119], v[196:199], v[212:215], v[116:119]
	v_mfma_f32_16x16x32_bf16 v[112:115], v[204:207], v[212:215], v[112:115]
	v_mfma_f32_16x16x32_bf16 v[100:103], v[196:199], v[220:223], v[100:103]
	v_mfma_f32_16x16x32_bf16 v[96:99], v[204:207], v[220:223], v[96:99]
	v_mfma_f32_16x16x32_bf16 v[84:87], v[196:199], v[228:231], v[84:87]
	v_mfma_f32_16x16x32_bf16 v[80:83], v[204:207], v[228:231], v[80:83]
	v_mfma_f32_16x16x32_bf16 v[68:71], v[196:199], v[236:239], v[68:71]
	v_mfma_f32_16x16x32_bf16 v[64:67], v[204:207], v[236:239], v[64:67]
	s_setprio 0
	s_barrier
; #define PG8_STAGE(bufoff, gbase, voff) do { _Pragma("unroll") for (int _i = 0; _i < 2; ++_i) \
;         __builtin_amdgcn_global_load_lds((const unsigned*)((const char*)(gbase) + (voff)[_i]), (LAS unsigned*)(lds + (bufoff) + ldsw + _i * 8192), 16, 0, 0); } while (0)
; #define PG8_LDA(dst, b, h) do { _Pragma("unroll") for (int m = 0; m < 4; ++m) _Pragma("unroll") for (int k = 0; k < 2; ++k) dst[m][k] = *(const LAS bf16x8*)(lds + PG8_SA(b, h) + aoff + m * 2048 + k * 1024); } while (0)
; #define PG8_MMA(ai, bj, At, Bt) do { __builtin_amdgcn_s_setprio(1); _Pragma("unroll") for (int m = 0; m < 4; ++m) _Pragma("unroll") for (int n = 0; n < 2; ++n) _Pragma("unroll") for (int k = 0; k < 2; ++k) \
;         acc[ai][bj][m][n] = __builtin_amdgcn_mfma_f32_16x16x32_bf16(Bt[n][k], At[m][k], acc[ai][bj][m][n], 0, 0, 0); __builtin_amdgcn_s_setprio(0); } while (0)
; #define PG8_WAIT_V(n) asm volatile("s_waitcnt vmcnt(" #n ")" ::: "memory")
; #define PG8_WAIT_L(n) asm volatile("s_waitcnt lgkmcnt(" #n ")" ::: "memory")
; #define PG8_BAR __builtin_amdgcn_s_barrier()
; #define PG8_SCHED __builtin_amdgcn_sched_barrier(0)
; template <class Epi, class Sched>
; __device__ __forceinline__ void gemm_phase(LAS unsigned char* lds, const int K, const Sched& S, const Epi& E) {
;     ...
;             PG8_LDA(At, 1, 1); PG8_STAGE(PG8_SB(1, 0), b3, voffB); PG8_STAGE(PG8_SB(1, 1), b3 + hstep, voffB); PG8_STAGE(PG8_SA(1, 0), a3, voffA);
;             PG8_WAIT_V(8); PG8_WAIT_L(0); PG8_BAR; PG8_MMA(1, 0, At, B0); PG8_MMA(1, 1, At, B1); PG8_BAR; PG8_SCHED;
;         }
;         if (wr == 0) PG8_BAR;
	s_add_i32 s14, s16, s58
	v_lshl_add_u64 v[166:167], v[166:167], 0, s[36:37]
	s_mov_b32 m0, s14
	ds_read_b128 v[208:211], v147 offset:49152
	ds_read_b128 v[212:215], v147 offset:50176
	ds_read_b128 v[216:219], v147 offset:51200
	ds_read_b128 v[220:223], v147 offset:52224
	ds_read_b128 v[224:227], v147 offset:53248
	ds_read_b128 v[228:231], v147 offset:54272
	ds_read_b128 v[232:235], v147 offset:55296
	ds_read_b128 v[236:239], v147 offset:56320
	global_load_lds_dwordx4 v[166:167], off
	s_add_i32 m0, s14, 0x2000
	s_add_u32 s14, s38, 0x40080
	v_lshl_add_u64 v[166:167], v[180:181], 0, s[36:37]
	s_addc_u32 s15, s39, 0
	s_add_i32 s16, s17, s58
	global_load_lds_dwordx4 v[166:167], off
	v_lshl_add_u64 v[166:167], s[14:15], 0, v[140:141]
	s_mov_b32 m0, s16
	s_nop 0
	global_load_lds_dwordx4 v[166:167], off
	v_lshl_add_u64 v[166:167], s[14:15], 0, v[144:145]
	s_add_i32 m0, s16, 0x2000
	s_nop 0
	global_load_lds_dwordx4 v[166:167], off
	v_lshl_add_u64 v[166:167], v[182:183], 0, s[36:37]
	s_mov_b32 m0, s64
	s_nop 0
	global_load_lds_dwordx4 v[166:167], off
	v_lshl_add_u64 v[166:167], v[240:241], 0, s[36:37]
	s_mov_b32 m0, s65
	s_nop 0
	global_load_lds_dwordx4 v[166:167], off
	s_waitcnt vmcnt(8)
	s_waitcnt lgkmcnt(0)
	s_barrier
	s_setprio 1
	s_waitcnt lgkmcnt(0)
	v_mfma_f32_16x16x32_bf16 v[60:63], v[158:161], v[208:211], v[60:63]
	v_mfma_f32_16x16x32_bf16 v[56:59], v[184:187], v[208:211], v[56:59]
	v_mfma_f32_16x16x32_bf16 v[44:47], v[158:161], v[216:219], v[44:47]
	v_mfma_f32_16x16x32_bf16 v[40:43], v[184:187], v[216:219], v[40:43]
	v_mfma_f32_16x16x32_bf16 v[28:31], v[158:161], v[224:227], v[28:31]
	v_mfma_f32_16x16x32_bf16 v[24:27], v[184:187], v[224:227], v[24:27]
	v_mfma_f32_16x16x32_bf16 v[12:15], v[158:161], v[232:235], v[12:15]
	v_mfma_f32_16x16x32_bf16 v[8:11], v[184:187], v[232:235], v[8:11]
	v_mfma_f32_16x16x32_bf16 v[60:63], v[162:165], v[212:215], v[60:63]
	v_mfma_f32_16x16x32_bf16 v[56:59], v[188:191], v[212:215], v[56:59]
	v_mfma_f32_16x16x32_bf16 v[44:47], v[162:165], v[220:223], v[44:47]
	v_mfma_f32_16x16x32_bf16 v[40:43], v[188:191], v[220:223], v[40:43]
	v_mfma_f32_16x16x32_bf16 v[28:31], v[162:165], v[228:231], v[28:31]
	v_mfma_f32_16x16x32_bf16 v[24:27], v[188:191], v[228:231], v[24:27]
	v_mfma_f32_16x16x32_bf16 v[12:15], v[162:165], v[236:239], v[12:15]
	v_mfma_f32_16x16x32_bf16 v[8:11], v[188:191], v[236:239], v[8:11]
	v_mfma_f32_16x16x32_bf16 v[52:55], v[192:195], v[208:211], v[52:55]
	v_mfma_f32_16x16x32_bf16 v[48:51], v[200:203], v[208:211], v[48:51]
	v_mfma_f32_16x16x32_bf16 v[36:39], v[192:195], v[216:219], v[36:39]
	v_mfma_f32_16x16x32_bf16 v[32:35], v[200:203], v[216:219], v[32:35]
	v_mfma_f32_16x16x32_bf16 v[20:23], v[192:195], v[224:227], v[20:23]
	v_mfma_f32_16x16x32_bf16 v[16:19], v[200:203], v[224:227], v[16:19]
	v_mfma_f32_16x16x32_bf16 v[4:7], v[192:195], v[232:235], v[4:7]
	v_mfma_f32_16x16x32_bf16 v[0:3], v[200:203], v[232:235], v[0:3]
	v_mfma_f32_16x16x32_bf16 v[52:55], v[196:199], v[212:215], v[52:55]
	v_mfma_f32_16x16x32_bf16 v[48:51], v[204:207], v[212:215], v[48:51]
	v_mfma_f32_16x16x32_bf16 v[36:39], v[196:199], v[220:223], v[36:39]
	v_mfma_f32_16x16x32_bf16 v[32:35], v[204:207], v[220:223], v[32:35]
	v_mfma_f32_16x16x32_bf16 v[20:23], v[196:199], v[228:231], v[20:23]
	v_mfma_f32_16x16x32_bf16 v[16:19], v[204:207], v[228:231], v[16:19]
	v_mfma_f32_16x16x32_bf16 v[4:7], v[196:199], v[236:239], v[4:7]
	v_mfma_f32_16x16x32_bf16 v[0:3], v[204:207], v[236:239], v[0:3]
	s_setprio 0
	s_barrier
	s_add_i32 s13, s13, 2
	s_add_u32 s8, s8, 0x100
	s_addc_u32 s9, s9, 0
	s_add_u32 s11, s11, 0x100
	s_addc_u32 s12, s12, 0
	s_cmp_gt_u32 s13, 13
	s_cbranch_scc0 .LBB0_403
	s_and_b64 vcc, exec, s[42:43]
	s_cbranch_vccz .LBB0_406
	s_barrier

; #define PG8_STAGE(bufoff, gbase, voff) do { _Pragma("unroll") for (int _i = 0; _i < 2; ++_i) \
;         __builtin_amdgcn_global_load_lds((const unsigned*)((const char*)(gbase) + (voff)[_i]), (LAS unsigned*)(lds + (bufoff) + ldsw + _i * 8192), 16, 0, 0); } while (0)
; #define PG8_LDA(dst, b, h) do { _Pragma("unroll") for (int m = 0; m < 4; ++m) _Pragma("unroll") for (int k = 0; k < 2; ++k) dst[m][k] = *(const LAS bf16x8*)(lds + PG8_SA(b, h) + aoff + m * 2048 + k * 1024); } while (0)
; #define PG8_LDB(dst, b, h) do { _Pragma("unroll") for (int n = 0; n < 2; ++n) _Pragma("unroll") for (int k = 0; k < 2; ++k) dst[n][k] = *(const LAS bf16x8*)(lds + PG8_SB(b, h) + boff + n * 2048 + k * 1024); } while (0)
; #define PG8_MMA(ai, bj, At, Bt) do { __builtin_amdgcn_s_setprio(1); _Pragma("unroll") for (int m = 0; m < 4; ++m) _Pragma("unroll") for (int n = 0; n < 2; ++n) _Pragma("unroll") for (int k = 0; k < 2; ++k) \
;         acc[ai][bj][m][n] = __builtin_amdgcn_mfma_f32_16x16x32_bf16(Bt[n][k], At[m][k], acc[ai][bj][m][n], 0, 0, 0); __builtin_amdgcn_s_setprio(0); } while (0)
; #define PG8_WAIT_V(n) asm volatile("s_waitcnt vmcnt(" #n ")" ::: "memory")
; #define PG8_WAIT_L(n) asm volatile("s_waitcnt lgkmcnt(" #n ")" ::: "memory")
; #define PG8_BAR __builtin_amdgcn_s_barrier()
; #define PG8_SCHED __builtin_amdgcn_sched_barrier(0)
; template <class Epi, class Sched>
; __device__ __forceinline__ void gemm_phase(LAS unsigned char* lds, const int K, const Sched& S, const Epi& E) {
;     ...
;             const bool last = (t == nt - 2);
;             const char* a1 = cA + (size_t)(t + 1) * kstep;
;             const char* a2 = last ? nA : cA + (size_t)(t + 2) * kstep; const char* b2 = last ? nB : cB + (size_t)(t + 2) * kstep;
;             const char* a3 = a2 + kstep; const char* b3 = b2 + kstep;
;             PG8_LDB(B0, 0, 0); PG8_LDB(B1, 0, 1); PG8_SCHED; PG8_LDA(At, 0, 0); PG8_STAGE(PG8_SA(1, 1), a1 + hstep, voffA);
;             PG8_WAIT_V(8); PG8_WAIT_L(0); PG8_BAR; PG8_MMA(0, 0, At, B0); PG8_MMA(0, 1, At, B1); PG8_BAR; PG8_SCHED;
;             PG8_LDA(At, 0, 1); PG8_STAGE(PG8_SB(0, 0), b2, voffB); PG8_STAGE(PG8_SB(0, 1), b2 + hstep, voffB); PG8_STAGE(PG8_SA(0, 0), a2, voffA);
;             PG8_WAIT_V(8); PG8_WAIT_L(0); PG8_BAR; PG8_MMA(1, 0, At, B0); PG8_MMA(1, 1, At, B1); PG8_BAR; PG8_SCHED;
.LBB0_511:
	s_add_i32 s14, s8, 0xfaf9e080
	s_cmp_lg_u32 s13, 60
	s_cselect_b32 s14, s14, 0
	s_add_u32 s40, s28, s14
	s_addc_u32 s41, s29, 0
	s_add_i32 s15, 0, 0x10000
	s_add_u32 s38, s34, s14
	s_addc_u32 s39, s35, 0
	s_add_i32 s16, 0, 0x14000
	v_add_u32_e32 v164, s15, v145
	v_add_u32_e32 v180, s16, v145
	ds_read_b128 v[152:155], v164
	ds_read_b128 v[156:159], v164 offset:1024
	ds_read_b128 v[160:163], v164 offset:2048
	ds_read_b128 v[164:167], v164 offset:3072
	ds_read_b128 v[184:187], v180
	ds_read_b128 v[188:191], v180 offset:1024
	ds_read_b128 v[192:195], v180 offset:2048
	ds_read_b128 v[196:199], v180 offset:3072
	v_lshl_add_u64 v[180:181], v[146:147], 0, s[8:9]
	s_add_i32 m0, s2, 0xc000
	ds_read_b128 v[200:203], v151
	ds_read_b128 v[204:207], v151 offset:1024
	ds_read_b128 v[208:211], v151 offset:2048
	ds_read_b128 v[212:215], v151 offset:3072
	ds_read_b128 v[216:219], v151 offset:4096
	ds_read_b128 v[220:223], v151 offset:5120
	ds_read_b128 v[224:227], v151 offset:6144
	ds_read_b128 v[228:231], v151 offset:7168
	global_load_lds_dwordx4 v[180:181], off
	v_lshl_add_u64 v[180:181], v[148:149], 0, s[8:9]
	s_add_i32 m0, s2, 0xe000
	s_nop 0
	global_load_lds_dwordx4 v[180:181], off
	s_waitcnt vmcnt(8)
	s_waitcnt lgkmcnt(0)
	s_barrier
	s_setprio 1
	s_waitcnt lgkmcnt(0)
	v_mfma_f32_16x16x32_bf16 v[124:127], v[152:155], v[200:203], v[124:127]
	v_mfma_f32_16x16x32_bf16 v[120:123], v[160:163], v[200:203], v[120:123]
	v_mfma_f32_16x16x32_bf16 v[108:111], v[152:155], v[208:211], v[108:111]
	v_mfma_f32_16x16x32_bf16 v[104:107], v[160:163], v[208:211], v[104:107]
	v_mfma_f32_16x16x32_bf16 v[92:95], v[152:155], v[216:219], v[92:95]
	v_mfma_f32_16x16x32_bf16 v[88:91], v[160:163], v[216:219], v[88:91]
	v_mfma_f32_16x16x32_bf16 v[76:79], v[152:155], v[224:227], v[76:79]
	v_mfma_f32_16x16x32_bf16 v[72:75], v[160:163], v[224:227], v[72:75]
	v_mfma_f32_16x16x32_bf16 v[124:127], v[156:159], v[204:207], v[124:127]
	v_mfma_f32_16x16x32_bf16 v[120:123], v[164:167], v[204:207], v[120:123]
	v_mfma_f32_16x16x32_bf16 v[108:111], v[156:159], v[212:215], v[108:111]
	v_mfma_f32_16x16x32_bf16 v[104:107], v[164:167], v[212:215], v[104:107]
	v_mfma_f32_16x16x32_bf16 v[92:95], v[156:159], v[220:223], v[92:95]
	v_mfma_f32_16x16x32_bf16 v[88:91], v[164:167], v[220:223], v[88:91]
	v_mfma_f32_16x16x32_bf16 v[76:79], v[156:159], v[228:231], v[76:79]
	v_mfma_f32_16x16x32_bf16 v[72:75], v[164:167], v[228:231], v[72:75]
	v_mfma_f32_16x16x32_bf16 v[116:119], v[184:187], v[200:203], v[116:119]
	v_mfma_f32_16x16x32_bf16 v[112:115], v[192:195], v[200:203], v[112:115]
	v_mfma_f32_16x16x32_bf16 v[100:103], v[184:187], v[208:211], v[100:103]
	v_mfma_f32_16x16x32_bf16 v[96:99], v[192:195], v[208:211], v[96:99]
	v_mfma_f32_16x16x32_bf16 v[84:87], v[184:187], v[216:219], v[84:87]
	v_mfma_f32_16x16x32_bf16 v[80:83], v[192:195], v[216:219], v[80:83]
	v_mfma_f32_16x16x32_bf16 v[68:71], v[184:187], v[224:227], v[68:71]
	v_mfma_f32_16x16x32_bf16 v[64:67], v[192:195], v[224:227], v[64:67]
	v_mfma_f32_16x16x32_bf16 v[116:119], v[188:191], v[204:207], v[116:119]
	v_mfma_f32_16x16x32_bf16 v[112:115], v[196:199], v[204:207], v[112:115]
	v_mfma_f32_16x16x32_bf16 v[100:103], v[188:191], v[212:215], v[100:103]
	v_mfma_f32_16x16x32_bf16 v[96:99], v[196:199], v[212:215], v[96:99]
	v_mfma_f32_16x16x32_bf16 v[84:87], v[188:191], v[220:223], v[84:87]
	v_mfma_f32_16x16x32_bf16 v[80:83], v[196:199], v[220:223], v[80:83]
	v_mfma_f32_16x16x32_bf16 v[68:71], v[188:191], v[228:231], v[68:71]
	v_mfma_f32_16x16x32_bf16 v[64:67], v[196:199], v[228:231], v[64:67]
	s_setprio 0
	s_barrier
	s_add_i32 s14, s15, s1
	v_lshl_add_u64 v[180:181], s[38:39], 0, v[128:129]
	s_mov_b32 m0, s14
	ds_read_b128 v[200:203], v151 offset:16384
	ds_read_b128 v[204:207], v151 offset:17408
	ds_read_b128 v[208:211], v151 offset:18432
	ds_read_b128 v[212:215], v151 offset:19456
	ds_read_b128 v[216:219], v151 offset:20480
	ds_read_b128 v[220:223], v151 offset:21504
	ds_read_b128 v[224:227], v151 offset:22528
	ds_read_b128 v[228:231], v151 offset:23552
	global_load_lds_dwordx4 v[180:181], off
	s_add_i32 m0, s14, 0x2000
	s_add_u32 s14, s38, 0x100000
	v_lshl_add_u64 v[182:183], s[38:39], 0, v[138:139]
	s_addc_u32 s15, s39, 0
	s_add_i32 s16, s16, s1
	global_load_lds_dwordx4 v[182:183], off
	v_lshl_add_u64 v[232:233], s[14:15], 0, v[128:129]
	s_mov_b32 m0, s16
	v_lshl_add_u64 v[234:235], s[40:41], 0, v[140:141]
	global_load_lds_dwordx4 v[232:233], off
	v_lshl_add_u64 v[232:233], s[14:15], 0, v[138:139]
	s_add_i32 m0, s16, 0x2000
	s_nop 0
	global_load_lds_dwordx4 v[232:233], off
	v_lshl_add_u64 v[232:233], s[40:41], 0, v[142:143]
	s_mov_b32 m0, s2
	s_nop 0
	global_load_lds_dwordx4 v[232:233], off
	s_mov_b32 m0, s3
	s_nop 0
	global_load_lds_dwordx4 v[234:235], off
	s_waitcnt vmcnt(8)
	s_waitcnt lgkmcnt(0)
	s_barrier
; #define PG8_STAGE(bufoff, gbase, voff) do { _Pragma("unroll") for (int _i = 0; _i < 2; ++_i) \
;         __builtin_amdgcn_global_load_lds((const unsigned*)((const char*)(gbase) + (voff)[_i]), (LAS unsigned*)(lds + (bufoff) + ldsw + _i * 8192), 16, 0, 0); } while (0)
; #define PG8_LDA(dst, b, h) do { _Pragma("unroll") for (int m = 0; m < 4; ++m) _Pragma("unroll") for (int k = 0; k < 2; ++k) dst[m][k] = *(const LAS bf16x8*)(lds + PG8_SA(b, h) + aoff + m * 2048 + k * 1024); } while (0)
; #define PG8_LDB(dst, b, h) do { _Pragma("unroll") for (int n = 0; n < 2; ++n) _Pragma("unroll") for (int k = 0; k < 2; ++k) dst[n][k] = *(const LAS bf16x8*)(lds + PG8_SB(b, h) + boff + n * 2048 + k * 1024); } while (0)
; #define PG8_MMA(ai, bj, At, Bt) do { __builtin_amdgcn_s_setprio(1); _Pragma("unroll") for (int m = 0; m < 4; ++m) _Pragma("unroll") for (int n = 0; n < 2; ++n) _Pragma("unroll") for (int k = 0; k < 2; ++k) \
;         acc[ai][bj][m][n] = __builtin_amdgcn_mfma_f32_16x16x32_bf16(Bt[n][k], At[m][k], acc[ai][bj][m][n], 0, 0, 0); __builtin_amdgcn_s_setprio(0); } while (0)
; #define PG8_WAIT_V(n) asm volatile("s_waitcnt vmcnt(" #n ")" ::: "memory")
; #define PG8_WAIT_L(n) asm volatile("s_waitcnt lgkmcnt(" #n ")" ::: "memory")
; #define PG8_BAR __builtin_amdgcn_s_barrier()
; #define PG8_SCHED __builtin_amdgcn_sched_barrier(0)
; template <class Epi, class Sched>
; __device__ __forceinline__ void gemm_phase(LAS unsigned char* lds, const int K, const Sched& S, const Epi& E) {
;     ...
;             PG8_WAIT_V(8); PG8_WAIT_L(0); PG8_BAR; PG8_MMA(1, 0, At, B0); PG8_MMA(1, 1, At, B1); PG8_BAR; PG8_SCHED;
;             PG8_LDB(B0, 1, 0); PG8_LDB(B1, 1, 1); PG8_SCHED; PG8_LDA(At, 1, 0); PG8_STAGE(PG8_SA(0, 1), a2 + hstep, voffA);
;             PG8_WAIT_V(8); PG8_WAIT_L(0); PG8_BAR; PG8_MMA(0, 0, At, B0); PG8_MMA(0, 1, At, B1); PG8_BAR; PG8_SCHED;
	s_setprio 1
	s_waitcnt lgkmcnt(0)
	v_mfma_f32_16x16x32_bf16 v[60:63], v[152:155], v[200:203], v[60:63]
	v_mfma_f32_16x16x32_bf16 v[56:59], v[160:163], v[200:203], v[56:59]
	v_mfma_f32_16x16x32_bf16 v[44:47], v[152:155], v[208:211], v[44:47]
	v_mfma_f32_16x16x32_bf16 v[40:43], v[160:163], v[208:211], v[40:43]
	v_mfma_f32_16x16x32_bf16 v[28:31], v[152:155], v[216:219], v[28:31]
	v_mfma_f32_16x16x32_bf16 v[24:27], v[160:163], v[216:219], v[24:27]
	v_mfma_f32_16x16x32_bf16 v[12:15], v[152:155], v[224:227], v[12:15]
	v_mfma_f32_16x16x32_bf16 v[8:11], v[160:163], v[224:227], v[8:11]
	v_mfma_f32_16x16x32_bf16 v[60:63], v[156:159], v[204:207], v[60:63]
	v_mfma_f32_16x16x32_bf16 v[56:59], v[164:167], v[204:207], v[56:59]
	v_mfma_f32_16x16x32_bf16 v[44:47], v[156:159], v[212:215], v[44:47]
	v_mfma_f32_16x16x32_bf16 v[40:43], v[164:167], v[212:215], v[40:43]
	v_mfma_f32_16x16x32_bf16 v[28:31], v[156:159], v[220:223], v[28:31]
	v_mfma_f32_16x16x32_bf16 v[24:27], v[164:167], v[220:223], v[24:27]
	v_mfma_f32_16x16x32_bf16 v[12:15], v[156:159], v[228:231], v[12:15]
	v_mfma_f32_16x16x32_bf16 v[8:11], v[164:167], v[228:231], v[8:11]
	v_mfma_f32_16x16x32_bf16 v[52:55], v[184:187], v[200:203], v[52:55]
	v_mfma_f32_16x16x32_bf16 v[48:51], v[192:195], v[200:203], v[48:51]
	v_mfma_f32_16x16x32_bf16 v[36:39], v[184:187], v[208:211], v[36:39]
	v_mfma_f32_16x16x32_bf16 v[32:35], v[192:195], v[208:211], v[32:35]
	v_mfma_f32_16x16x32_bf16 v[20:23], v[184:187], v[216:219], v[20:23]
	v_mfma_f32_16x16x32_bf16 v[16:19], v[192:195], v[216:219], v[16:19]
	v_mfma_f32_16x16x32_bf16 v[4:7], v[184:187], v[224:227], v[4:7]
	v_mfma_f32_16x16x32_bf16 v[0:3], v[192:195], v[224:227], v[0:3]
	v_mfma_f32_16x16x32_bf16 v[52:55], v[188:191], v[204:207], v[52:55]
	v_mfma_f32_16x16x32_bf16 v[48:51], v[196:199], v[204:207], v[48:51]
	v_mfma_f32_16x16x32_bf16 v[36:39], v[188:191], v[212:215], v[36:39]
	v_mfma_f32_16x16x32_bf16 v[32:35], v[196:199], v[212:215], v[32:35]
	v_mfma_f32_16x16x32_bf16 v[20:23], v[188:191], v[220:223], v[20:23]
	v_mfma_f32_16x16x32_bf16 v[16:19], v[196:199], v[220:223], v[16:19]
	v_mfma_f32_16x16x32_bf16 v[4:7], v[188:191], v[228:231], v[4:7]
	v_mfma_f32_16x16x32_bf16 v[0:3], v[196:199], v[228:231], v[0:3]
	s_setprio 0
	s_barrier
	s_add_i32 s16, 0, 0x18000
	s_add_i32 s17, 0, 0x1c000
	v_add_u32_e32 v164, s16, v145
	v_add_u32_e32 v196, s17, v145
	ds_read_b128 v[152:155], v164
	ds_read_b128 v[156:159], v164 offset:1024
	ds_read_b128 v[160:163], v164 offset:2048
	ds_read_b128 v[164:167], v164 offset:3072
	ds_read_b128 v[184:187], v196
	ds_read_b128 v[188:191], v196 offset:1024
	ds_read_b128 v[192:195], v196 offset:2048
	ds_read_b128 v[196:199], v196 offset:3072
	s_add_u32 s14, s40, 0x100000
	s_addc_u32 s15, s41, 0
	s_mov_b32 m0, s4
	v_lshl_add_u64 v[236:237], s[14:15], 0, v[142:143]
	ds_read_b128 v[200:203], v151 offset:32768
	ds_read_b128 v[204:207], v151 offset:33792
	ds_read_b128 v[208:211], v151 offset:34816
	ds_read_b128 v[212:215], v151 offset:35840
	ds_read_b128 v[216:219], v151 offset:36864
	ds_read_b128 v[220:223], v151 offset:37888
	ds_read_b128 v[224:227], v151 offset:38912
	ds_read_b128 v[228:231], v151 offset:39936
	global_load_lds_dwordx4 v[236:237], off
	v_lshl_add_u64 v[236:237], s[14:15], 0, v[140:141]
	s_mov_b32 m0, s5
	s_nop 0
	global_load_lds_dwordx4 v[236:237], off
	s_waitcnt vmcnt(8)
	s_waitcnt lgkmcnt(0)
	s_barrier
	s_setprio 1
	s_waitcnt lgkmcnt(0)
	v_mfma_f32_16x16x32_bf16 v[124:127], v[152:155], v[200:203], v[124:127]
	v_mfma_f32_16x16x32_bf16 v[120:123], v[160:163], v[200:203], v[120:123]
	v_mfma_f32_16x16x32_bf16 v[108:111], v[152:155], v[208:211], v[108:111]
	v_mfma_f32_16x16x32_bf16 v[104:107], v[160:163], v[208:211], v[104:107]
	v_mfma_f32_16x16x32_bf16 v[92:95], v[152:155], v[216:219], v[92:95]
	v_mfma_f32_16x16x32_bf16 v[88:91], v[160:163], v[216:219], v[88:91]
	v_mfma_f32_16x16x32_bf16 v[76:79], v[152:155], v[224:227], v[76:79]
	v_mfma_f32_16x16x32_bf16 v[72:75], v[160:163], v[224:227], v[72:75]
	v_mfma_f32_16x16x32_bf16 v[124:127], v[156:159], v[204:207], v[124:127]
	v_mfma_f32_16x16x32_bf16 v[120:123], v[164:167], v[204:207], v[120:123]
	v_mfma_f32_16x16x32_bf16 v[108:111], v[156:159], v[212:215], v[108:111]
	v_mfma_f32_16x16x32_bf16 v[104:107], v[164:167], v[212:215], v[104:107]
	v_mfma_f32_16x16x32_bf16 v[92:95], v[156:159], v[220:223], v[92:95]
	v_mfma_f32_16x16x32_bf16 v[88:91], v[164:167], v[220:223], v[88:91]
	v_mfma_f32_16x16x32_bf16 v[76:79], v[156:159], v[228:231], v[76:79]
	v_mfma_f32_16x16x32_bf16 v[72:75], v[164:167], v[228:231], v[72:75]
	v_mfma_f32_16x16x32_bf16 v[116:119], v[184:187], v[200:203], v[116:119]
	v_mfma_f32_16x16x32_bf16 v[112:115], v[192:195], v[200:203], v[112:115]
	v_mfma_f32_16x16x32_bf16 v[100:103], v[184:187], v[208:211], v[100:103]
	v_mfma_f32_16x16x32_bf16 v[96:99], v[192:195], v[208:211], v[96:99]
	v_mfma_f32_16x16x32_bf16 v[84:87], v[184:187], v[216:219], v[84:87]
	v_mfma_f32_16x16x32_bf16 v[80:83], v[192:195], v[216:219], v[80:83]
	v_mfma_f32_16x16x32_bf16 v[68:71], v[184:187], v[224:227], v[68:71]
	v_mfma_f32_16x16x32_bf16 v[64:67], v[192:195], v[224:227], v[64:67]
	v_mfma_f32_16x16x32_bf16 v[116:119], v[188:191], v[204:207], v[116:119]
	v_mfma_f32_16x16x32_bf16 v[112:115], v[196:199], v[204:207], v[112:115]
	v_mfma_f32_16x16x32_bf16 v[100:103], v[188:191], v[212:215], v[100:103]
	v_mfma_f32_16x16x32_bf16 v[96:99], v[196:199], v[212:215], v[96:99]
	v_mfma_f32_16x16x32_bf16 v[84:87], v[188:191], v[220:223], v[84:87]
	v_mfma_f32_16x16x32_bf16 v[80:83], v[196:199], v[220:223], v[80:83]
	v_mfma_f32_16x16x32_bf16 v[68:71], v[188:191], v[228:231], v[68:71]
	v_mfma_f32_16x16x32_bf16 v[64:67], v[196:199], v[228:231], v[64:67]
	s_setprio 0
	s_barrier
; #define PG8_STAGE(bufoff, gbase, voff) do { _Pragma("unroll") for (int _i = 0; _i < 2; ++_i) \
;         __builtin_amdgcn_global_load_lds((const unsigned*)((const char*)(gbase) + (voff)[_i]), (LAS unsigned*)(lds + (bufoff) + ldsw + _i * 8192), 16, 0, 0); } while (0)
; #define PG8_LDA(dst, b, h) do { _Pragma("unroll") for (int m = 0; m < 4; ++m) _Pragma("unroll") for (int k = 0; k < 2; ++k) dst[m][k] = *(const LAS bf16x8*)(lds + PG8_SA(b, h) + aoff + m * 2048 + k * 1024); } while (0)
; #define PG8_MMA(ai, bj, At, Bt) do { __builtin_amdgcn_s_setprio(1); _Pragma("unroll") for (int m = 0; m < 4; ++m) _Pragma("unroll") for (int n = 0; n < 2; ++n) _Pragma("unroll") for (int k = 0; k < 2; ++k) \
;         acc[ai][bj][m][n] = __builtin_amdgcn_mfma_f32_16x16x32_bf16(Bt[n][k], At[m][k], acc[ai][bj][m][n], 0, 0, 0); __builtin_amdgcn_s_setprio(0); } while (0)
; #define PG8_WAIT_V(n) asm volatile("s_waitcnt vmcnt(" #n ")" ::: "memory")
; #define PG8_WAIT_L(n) asm volatile("s_waitcnt lgkmcnt(" #n ")" ::: "memory")
; #define PG8_BAR __builtin_amdgcn_s_barrier()
; #define PG8_SCHED __builtin_amdgcn_sched_barrier(0)
; template <class Epi, class Sched>
; __device__ __forceinline__ void gemm_phase(LAS unsigned char* lds, const int K, const Sched& S, const Epi& E) {
;     ...
;             PG8_LDA(At, 1, 1); PG8_STAGE(PG8_SB(1, 0), b3, voffB); PG8_STAGE(PG8_SB(1, 1), b3 + hstep, voffB); PG8_STAGE(PG8_SA(1, 0), a3, voffA);
;             PG8_WAIT_V(8); PG8_WAIT_L(0); PG8_BAR; PG8_MMA(1, 0, At, B0); PG8_MMA(1, 1, At, B1); PG8_BAR; PG8_SCHED;
;         }
;         if (wr == 0) PG8_BAR;
	s_add_i32 s14, s16, s1
	v_lshl_add_u64 v[180:181], v[180:181], 0, s[36:37]
	s_mov_b32 m0, s14
	ds_read_b128 v[200:203], v151 offset:49152
	ds_read_b128 v[204:207], v151 offset:50176
	ds_read_b128 v[208:211], v151 offset:51200
	ds_read_b128 v[212:215], v151 offset:52224
	ds_read_b128 v[216:219], v151 offset:53248
	ds_read_b128 v[220:223], v151 offset:54272
	ds_read_b128 v[224:227], v151 offset:55296
	ds_read_b128 v[228:231], v151 offset:56320
	global_load_lds_dwordx4 v[180:181], off
	s_add_i32 m0, s14, 0x2000
	s_add_u32 s14, s38, 0x100080
	v_lshl_add_u64 v[180:181], v[182:183], 0, s[36:37]
	s_addc_u32 s15, s39, 0
	s_add_i32 s16, s17, s1
	global_load_lds_dwordx4 v[180:181], off
	v_lshl_add_u64 v[180:181], s[14:15], 0, v[128:129]
	s_mov_b32 m0, s16
	s_nop 0
	global_load_lds_dwordx4 v[180:181], off
	v_lshl_add_u64 v[180:181], s[14:15], 0, v[138:139]
	s_add_i32 m0, s16, 0x2000
	s_nop 0
	global_load_lds_dwordx4 v[180:181], off
	v_lshl_add_u64 v[180:181], v[232:233], 0, s[36:37]
	s_mov_b32 m0, s11
	s_nop 0
	global_load_lds_dwordx4 v[180:181], off
	v_lshl_add_u64 v[180:181], v[234:235], 0, s[36:37]
	s_mov_b32 m0, s12
	s_nop 0
	global_load_lds_dwordx4 v[180:181], off
	s_waitcnt vmcnt(8)
	s_waitcnt lgkmcnt(0)
	s_barrier
	s_setprio 1
	s_waitcnt lgkmcnt(0)
	v_mfma_f32_16x16x32_bf16 v[60:63], v[152:155], v[200:203], v[60:63]
	v_mfma_f32_16x16x32_bf16 v[56:59], v[160:163], v[200:203], v[56:59]
	v_mfma_f32_16x16x32_bf16 v[44:47], v[152:155], v[208:211], v[44:47]
	v_mfma_f32_16x16x32_bf16 v[40:43], v[160:163], v[208:211], v[40:43]
	v_mfma_f32_16x16x32_bf16 v[28:31], v[152:155], v[216:219], v[28:31]
	v_mfma_f32_16x16x32_bf16 v[24:27], v[160:163], v[216:219], v[24:27]
	v_mfma_f32_16x16x32_bf16 v[12:15], v[152:155], v[224:227], v[12:15]
	v_mfma_f32_16x16x32_bf16 v[8:11], v[160:163], v[224:227], v[8:11]
	v_mfma_f32_16x16x32_bf16 v[60:63], v[156:159], v[204:207], v[60:63]
	v_mfma_f32_16x16x32_bf16 v[56:59], v[164:167], v[204:207], v[56:59]
	v_mfma_f32_16x16x32_bf16 v[44:47], v[156:159], v[212:215], v[44:47]
	v_mfma_f32_16x16x32_bf16 v[40:43], v[164:167], v[212:215], v[40:43]
	v_mfma_f32_16x16x32_bf16 v[28:31], v[156:159], v[220:223], v[28:31]
	v_mfma_f32_16x16x32_bf16 v[24:27], v[164:167], v[220:223], v[24:27]
	v_mfma_f32_16x16x32_bf16 v[12:15], v[156:159], v[228:231], v[12:15]
	v_mfma_f32_16x16x32_bf16 v[8:11], v[164:167], v[228:231], v[8:11]
	v_mfma_f32_16x16x32_bf16 v[52:55], v[184:187], v[200:203], v[52:55]
	v_mfma_f32_16x16x32_bf16 v[48:51], v[192:195], v[200:203], v[48:51]
	v_mfma_f32_16x16x32_bf16 v[36:39], v[184:187], v[208:211], v[36:39]
	v_mfma_f32_16x16x32_bf16 v[32:35], v[192:195], v[208:211], v[32:35]
	v_mfma_f32_16x16x32_bf16 v[20:23], v[184:187], v[216:219], v[20:23]
	v_mfma_f32_16x16x32_bf16 v[16:19], v[192:195], v[216:219], v[16:19]
	v_mfma_f32_16x16x32_bf16 v[4:7], v[184:187], v[224:227], v[4:7]
	v_mfma_f32_16x16x32_bf16 v[0:3], v[192:195], v[224:227], v[0:3]
	v_mfma_f32_16x16x32_bf16 v[52:55], v[188:191], v[204:207], v[52:55]
	v_mfma_f32_16x16x32_bf16 v[48:51], v[196:199], v[204:207], v[48:51]
	v_mfma_f32_16x16x32_bf16 v[36:39], v[188:191], v[212:215], v[36:39]
	v_mfma_f32_16x16x32_bf16 v[32:35], v[196:199], v[212:215], v[32:35]
	v_mfma_f32_16x16x32_bf16 v[20:23], v[188:191], v[220:223], v[20:23]
	v_mfma_f32_16x16x32_bf16 v[16:19], v[196:199], v[220:223], v[16:19]
	v_mfma_f32_16x16x32_bf16 v[4:7], v[188:191], v[228:231], v[4:7]
	v_mfma_f32_16x16x32_bf16 v[0:3], v[196:199], v[228:231], v[0:3]
	s_setprio 0
	s_barrier
	s_add_i32 s13, s13, 2
	s_add_u32 s8, s8, 0x100
	s_addc_u32 s9, s9, 0
	s_cmp_gt_u32 s13, 61
	s_cbranch_scc0 .LBB0_511
	s_cmpk_lt_u32 s0, 0x100
	s_cbranch_scc0 .LBB0_514
	s_barrier

; #define PG8_STAGE(bufoff, gbase, voff) do { _Pragma("unroll") for (int _i = 0; _i < 2; ++_i) \
;         __builtin_amdgcn_global_load_lds((const unsigned*)((const char*)(gbase) + (voff)[_i]), (LAS unsigned*)(lds + (bufoff) + ldsw + _i * 8192), 16, 0, 0); } while (0)
; #define PG8_LDA(dst, b, h) do { _Pragma("unroll") for (int m = 0; m < 4; ++m) _Pragma("unroll") for (int k = 0; k < 2; ++k) dst[m][k] = *(const LAS bf16x8*)(lds + PG8_SA(b, h) + aoff + m * 2048 + k * 1024); } while (0)
; #define PG8_LDB(dst, b, h) do { _Pragma("unroll") for (int n = 0; n < 2; ++n) _Pragma("unroll") for (int k = 0; k < 2; ++k) dst[n][k] = *(const LAS bf16x8*)(lds + PG8_SB(b, h) + boff + n * 2048 + k * 1024); } while (0)
; #define PG8_MMA(ai, bj, At, Bt) do { __builtin_amdgcn_s_setprio(1); _Pragma("unroll") for (int m = 0; m < 4; ++m) _Pragma("unroll") for (int n = 0; n < 2; ++n) _Pragma("unroll") for (int k = 0; k < 2; ++k) \
;         acc[ai][bj][m][n] = __builtin_amdgcn_mfma_f32_16x16x32_bf16(Bt[n][k], At[m][k], acc[ai][bj][m][n], 0, 0, 0); __builtin_amdgcn_s_setprio(0); } while (0)
; #define PG8_WAIT_V(n) asm volatile("s_waitcnt vmcnt(" #n ")" ::: "memory")
; #define PG8_WAIT_L(n) asm volatile("s_waitcnt lgkmcnt(" #n ")" ::: "memory")
; #define PG8_BAR __builtin_amdgcn_s_barrier()
; #define PG8_SCHED __builtin_amdgcn_sched_barrier(0)
; template <class Epi, class Sched>
; __device__ __forceinline__ void gemm_phase(LAS unsigned char* lds, const int K, const Sched& S, const Epi& E) {
;     ...
;             const bool last = (t == nt - 2);
;             const char* a1 = cA + (size_t)(t + 1) * kstep;
;             const char* a2 = last ? nA : cA + (size_t)(t + 2) * kstep; const char* b2 = last ? nB : cB + (size_t)(t + 2) * kstep;
;             const char* a3 = a2 + kstep; const char* b3 = b2 + kstep;
;             PG8_LDB(B0, 0, 0); PG8_LDB(B1, 0, 1); PG8_SCHED; PG8_LDA(At, 0, 0); PG8_STAGE(PG8_SA(1, 1), a1 + hstep, voffA);
;             PG8_WAIT_V(8); PG8_WAIT_L(0); PG8_BAR; PG8_MMA(0, 0, At, B0); PG8_MMA(0, 1, At, B1); PG8_BAR; PG8_SCHED;
;             PG8_LDA(At, 0, 1); PG8_STAGE(PG8_SB(0, 0), b2, voffB); PG8_STAGE(PG8_SB(0, 1), b2 + hstep, voffB); PG8_STAGE(PG8_SA(0, 0), a2, voffA);
;             PG8_WAIT_V(8); PG8_WAIT_L(0); PG8_BAR; PG8_MMA(1, 0, At, B0); PG8_MMA(1, 1, At, B1); PG8_BAR; PG8_SCHED;
.LBB0_533:
	s_add_u32 s14, s50, s11
	s_addc_u32 s15, s51, 0
	s_add_u32 s16, s14, 0x100
	s_addc_u32 s17, s15, 0
	s_and_b64 s[12:13], s[54:55], exec
	s_cselect_b32 s59, s45, s17
	s_cselect_b32 s58, s44, s16
	s_add_u32 s11, s8, s11
	s_addc_u32 s12, s9, 0
	s_add_u32 s11, s11, 0x100
	s_addc_u32 s16, s12, 0
	s_add_i32 s21, 0, 0x10000
	s_and_b64 s[12:13], s[54:55], exec
	s_cselect_b32 s61, s47, s16
	s_cselect_b32 s60, s46, s11
	s_add_i32 s25, 0, 0x14000
	s_add_u32 s64, s14, 0x10080
	s_addc_u32 s65, s15, 0
	s_add_i32 s19, s21, s3
	s_add_i32 m0, s26, 0xc000
	s_add_i32 s28, s26, 0xe000
	s_add_i32 s15, s19, 0x2000
	v_add_u32_e32 v146, s21, v148
	s_add_u32 s62, s60, 0x10000
	ds_read_b128 v[152:155], v146
	ds_read_b128 v[156:159], v146 offset:1024
	ds_read_b128 v[160:163], v146 offset:2048
	ds_read_b128 v[164:167], v146 offset:3072
	v_add_u32_e32 v146, s25, v148
	s_addc_u32 s63, s61, 0
	s_add_i32 s17, s25, s3
	ds_read_b128 v[184:187], v146
	ds_read_b128 v[188:191], v146 offset:1024
	ds_read_b128 v[192:195], v146 offset:2048
	ds_read_b128 v[196:199], v146 offset:3072
	s_add_i32 s16, s17, 0x2000
	s_add_i32 s14, 0, 0x18000
	s_add_i32 s13, 0, 0x1c000
	s_add_u32 s56, s58, 0x10000
	s_addc_u32 s57, s59, 0
	s_add_i32 s12, s14, s3
	s_add_i32 s11, s12, 0x2000
	s_add_u32 s54, s60, 0x10080
	s_addc_u32 s55, s61, 0
	s_add_i32 s25, s13, s3
	s_add_i32 s21, s25, 0x2000
	v_lshl_add_u64 v[146:147], s[64:65], 0, v[144:145]
	ds_read_b128 v[200:203], v150
	ds_read_b128 v[204:207], v150 offset:1024
	ds_read_b128 v[208:211], v150 offset:2048
	ds_read_b128 v[212:215], v150 offset:3072
	ds_read_b128 v[216:219], v150 offset:4096
	ds_read_b128 v[220:223], v150 offset:5120
	ds_read_b128 v[224:227], v150 offset:6144
	ds_read_b128 v[228:231], v150 offset:7168
	global_load_lds_dwordx4 v[146:147], off
	v_lshl_add_u64 v[146:147], s[64:65], 0, v[140:141]
	s_mov_b32 m0, s28
	s_nop 0
	global_load_lds_dwordx4 v[146:147], off
	s_waitcnt vmcnt(8)
	s_waitcnt lgkmcnt(0)
	s_barrier
	s_setprio 1
	s_waitcnt lgkmcnt(0)
	v_mfma_f32_16x16x32_bf16 v[124:127], v[152:155], v[200:203], v[124:127]
	v_mfma_f32_16x16x32_bf16 v[120:123], v[160:163], v[200:203], v[120:123]
	v_mfma_f32_16x16x32_bf16 v[112:115], v[152:155], v[208:211], v[112:115]
	v_mfma_f32_16x16x32_bf16 v[104:107], v[160:163], v[208:211], v[104:107]
	v_mfma_f32_16x16x32_bf16 v[96:99], v[152:155], v[216:219], v[96:99]
	v_mfma_f32_16x16x32_bf16 v[88:91], v[160:163], v[216:219], v[88:91]
	v_mfma_f32_16x16x32_bf16 v[80:83], v[152:155], v[224:227], v[80:83]
	v_mfma_f32_16x16x32_bf16 v[72:75], v[160:163], v[224:227], v[72:75]
	v_mfma_f32_16x16x32_bf16 v[124:127], v[156:159], v[204:207], v[124:127]
	v_mfma_f32_16x16x32_bf16 v[120:123], v[164:167], v[204:207], v[120:123]
	v_mfma_f32_16x16x32_bf16 v[112:115], v[156:159], v[212:215], v[112:115]
	v_mfma_f32_16x16x32_bf16 v[104:107], v[164:167], v[212:215], v[104:107]
	v_mfma_f32_16x16x32_bf16 v[96:99], v[156:159], v[220:223], v[96:99]
	v_mfma_f32_16x16x32_bf16 v[88:91], v[164:167], v[220:223], v[88:91]
	v_mfma_f32_16x16x32_bf16 v[80:83], v[156:159], v[228:231], v[80:83]
	v_mfma_f32_16x16x32_bf16 v[72:75], v[164:167], v[228:231], v[72:75]
	v_mfma_f32_16x16x32_bf16 v[116:119], v[184:187], v[200:203], v[116:119]
	v_mfma_f32_16x16x32_bf16 v[108:111], v[192:195], v[200:203], v[108:111]
	v_mfma_f32_16x16x32_bf16 v[100:103], v[184:187], v[208:211], v[100:103]
	v_mfma_f32_16x16x32_bf16 v[92:95], v[192:195], v[208:211], v[92:95]
	v_mfma_f32_16x16x32_bf16 v[84:87], v[184:187], v[216:219], v[84:87]
	v_mfma_f32_16x16x32_bf16 v[76:79], v[192:195], v[216:219], v[76:79]
	v_mfma_f32_16x16x32_bf16 v[68:71], v[184:187], v[224:227], v[68:71]
	v_mfma_f32_16x16x32_bf16 v[64:67], v[192:195], v[224:227], v[64:67]
	v_mfma_f32_16x16x32_bf16 v[116:119], v[188:191], v[204:207], v[116:119]
	v_mfma_f32_16x16x32_bf16 v[108:111], v[196:199], v[204:207], v[108:111]
	v_mfma_f32_16x16x32_bf16 v[100:103], v[188:191], v[212:215], v[100:103]
	v_mfma_f32_16x16x32_bf16 v[92:95], v[196:199], v[212:215], v[92:95]
	v_mfma_f32_16x16x32_bf16 v[84:87], v[188:191], v[220:223], v[84:87]
	v_mfma_f32_16x16x32_bf16 v[76:79], v[196:199], v[220:223], v[76:79]
	v_mfma_f32_16x16x32_bf16 v[68:71], v[188:191], v[228:231], v[68:71]
	v_mfma_f32_16x16x32_bf16 v[64:67], v[196:199], v[228:231], v[64:67]
	s_setprio 0
	s_barrier
	s_mov_b32 m0, s19
	v_lshl_add_u64 v[146:147], s[60:61], 0, v[142:143]
	ds_read_b128 v[200:203], v150 offset:16384
	ds_read_b128 v[204:207], v150 offset:17408
	ds_read_b128 v[208:211], v150 offset:18432
	ds_read_b128 v[212:215], v150 offset:19456
	ds_read_b128 v[216:219], v150 offset:20480
	ds_read_b128 v[220:223], v150 offset:21504
	ds_read_b128 v[224:227], v150 offset:22528
	ds_read_b128 v[228:231], v150 offset:23552
	global_load_lds_dwordx4 v[146:147], off
	v_lshl_add_u64 v[180:181], s[60:61], 0, v[138:139]
	s_mov_b32 m0, s15
	v_lshl_add_u64 v[182:183], s[62:63], 0, v[142:143]
	global_load_lds_dwordx4 v[180:181], off
	s_mov_b32 m0, s17
	v_lshl_add_u64 v[232:233], s[58:59], 0, v[140:141]
	global_load_lds_dwordx4 v[182:183], off
	v_lshl_add_u64 v[182:183], s[62:63], 0, v[138:139]
	s_mov_b32 m0, s16
	s_nop 0
	global_load_lds_dwordx4 v[182:183], off
	v_lshl_add_u64 v[182:183], s[58:59], 0, v[144:145]
	s_mov_b32 m0, s26
	s_nop 0
	global_load_lds_dwordx4 v[182:183], off
	s_mov_b32 m0, s27
	s_nop 0
	global_load_lds_dwordx4 v[232:233], off
	s_waitcnt vmcnt(8)
	s_waitcnt lgkmcnt(0)
	s_barrier
; #define PG8_STAGE(bufoff, gbase, voff) do { _Pragma("unroll") for (int _i = 0; _i < 2; ++_i) \
;         __builtin_amdgcn_global_load_lds((const unsigned*)((const char*)(gbase) + (voff)[_i]), (LAS unsigned*)(lds + (bufoff) + ldsw + _i * 8192), 16, 0, 0); } while (0)
; #define PG8_LDA(dst, b, h) do { _Pragma("unroll") for (int m = 0; m < 4; ++m) _Pragma("unroll") for (int k = 0; k < 2; ++k) dst[m][k] = *(const LAS bf16x8*)(lds + PG8_SA(b, h) + aoff + m * 2048 + k * 1024); } while (0)
; #define PG8_LDB(dst, b, h) do { _Pragma("unroll") for (int n = 0; n < 2; ++n) _Pragma("unroll") for (int k = 0; k < 2; ++k) dst[n][k] = *(const LAS bf16x8*)(lds + PG8_SB(b, h) + boff + n * 2048 + k * 1024); } while (0)
; #define PG8_MMA(ai, bj, At, Bt) do { __builtin_amdgcn_s_setprio(1); _Pragma("unroll") for (int m = 0; m < 4; ++m) _Pragma("unroll") for (int n = 0; n < 2; ++n) _Pragma("unroll") for (int k = 0; k < 2; ++k) \
;         acc[ai][bj][m][n] = __builtin_amdgcn_mfma_f32_16x16x32_bf16(Bt[n][k], At[m][k], acc[ai][bj][m][n], 0, 0, 0); __builtin_amdgcn_s_setprio(0); } while (0)
; #define PG8_WAIT_V(n) asm volatile("s_waitcnt vmcnt(" #n ")" ::: "memory")
; #define PG8_WAIT_L(n) asm volatile("s_waitcnt lgkmcnt(" #n ")" ::: "memory")
; #define PG8_BAR __builtin_amdgcn_s_barrier()
; #define PG8_SCHED __builtin_amdgcn_sched_barrier(0)
; template <class Epi, class Sched>
; __device__ __forceinline__ void gemm_phase(LAS unsigned char* lds, const int K, const Sched& S, const Epi& E) {
;     ...
;             PG8_WAIT_V(8); PG8_WAIT_L(0); PG8_BAR; PG8_MMA(1, 0, At, B0); PG8_MMA(1, 1, At, B1); PG8_BAR; PG8_SCHED;
;             PG8_LDB(B0, 1, 0); PG8_LDB(B1, 1, 1); PG8_SCHED; PG8_LDA(At, 1, 0); PG8_STAGE(PG8_SA(0, 1), a2 + hstep, voffA);
;             PG8_WAIT_V(8); PG8_WAIT_L(0); PG8_BAR; PG8_MMA(0, 0, At, B0); PG8_MMA(0, 1, At, B1); PG8_BAR; PG8_SCHED;
	s_setprio 1
	s_waitcnt lgkmcnt(0)
	v_mfma_f32_16x16x32_bf16 v[60:63], v[152:155], v[200:203], v[60:63]
	v_mfma_f32_16x16x32_bf16 v[56:59], v[160:163], v[200:203], v[56:59]
	v_mfma_f32_16x16x32_bf16 v[48:51], v[152:155], v[208:211], v[48:51]
	v_mfma_f32_16x16x32_bf16 v[40:43], v[160:163], v[208:211], v[40:43]
	v_mfma_f32_16x16x32_bf16 v[32:35], v[152:155], v[216:219], v[32:35]
	v_mfma_f32_16x16x32_bf16 v[24:27], v[160:163], v[216:219], v[24:27]
	v_mfma_f32_16x16x32_bf16 v[16:19], v[152:155], v[224:227], v[16:19]
	v_mfma_f32_16x16x32_bf16 v[8:11], v[160:163], v[224:227], v[8:11]
	v_mfma_f32_16x16x32_bf16 v[60:63], v[156:159], v[204:207], v[60:63]
	v_mfma_f32_16x16x32_bf16 v[56:59], v[164:167], v[204:207], v[56:59]
	v_mfma_f32_16x16x32_bf16 v[48:51], v[156:159], v[212:215], v[48:51]
	v_mfma_f32_16x16x32_bf16 v[40:43], v[164:167], v[212:215], v[40:43]
	v_mfma_f32_16x16x32_bf16 v[32:35], v[156:159], v[220:223], v[32:35]
	v_mfma_f32_16x16x32_bf16 v[24:27], v[164:167], v[220:223], v[24:27]
	v_mfma_f32_16x16x32_bf16 v[16:19], v[156:159], v[228:231], v[16:19]
	v_mfma_f32_16x16x32_bf16 v[8:11], v[164:167], v[228:231], v[8:11]
	v_mfma_f32_16x16x32_bf16 v[52:55], v[184:187], v[200:203], v[52:55]
	v_mfma_f32_16x16x32_bf16 v[44:47], v[192:195], v[200:203], v[44:47]
	v_mfma_f32_16x16x32_bf16 v[36:39], v[184:187], v[208:211], v[36:39]
	v_mfma_f32_16x16x32_bf16 v[28:31], v[192:195], v[208:211], v[28:31]
	v_mfma_f32_16x16x32_bf16 v[20:23], v[184:187], v[216:219], v[20:23]
	v_mfma_f32_16x16x32_bf16 v[12:15], v[192:195], v[216:219], v[12:15]
	v_mfma_f32_16x16x32_bf16 v[4:7], v[184:187], v[224:227], v[4:7]
	v_mfma_f32_16x16x32_bf16 v[0:3], v[192:195], v[224:227], v[0:3]
	v_mfma_f32_16x16x32_bf16 v[52:55], v[188:191], v[204:207], v[52:55]
	v_mfma_f32_16x16x32_bf16 v[44:47], v[196:199], v[204:207], v[44:47]
	v_mfma_f32_16x16x32_bf16 v[36:39], v[188:191], v[212:215], v[36:39]
	v_mfma_f32_16x16x32_bf16 v[28:31], v[196:199], v[212:215], v[28:31]
	v_mfma_f32_16x16x32_bf16 v[20:23], v[188:191], v[220:223], v[20:23]
	v_mfma_f32_16x16x32_bf16 v[12:15], v[196:199], v[220:223], v[12:15]
	v_mfma_f32_16x16x32_bf16 v[4:7], v[188:191], v[228:231], v[4:7]
	v_mfma_f32_16x16x32_bf16 v[0:3], v[196:199], v[228:231], v[0:3]
	s_setprio 0
	s_barrier
	v_add_u32_e32 v151, s14, v148
	ds_read_b128 v[152:155], v151
	ds_read_b128 v[156:159], v151 offset:1024
	ds_read_b128 v[160:163], v151 offset:2048
	ds_read_b128 v[164:167], v151 offset:3072
	v_add_u32_e32 v151, s13, v148
	ds_read_b128 v[184:187], v151
	ds_read_b128 v[188:191], v151 offset:1024
	ds_read_b128 v[192:195], v151 offset:2048
	ds_read_b128 v[196:199], v151 offset:3072
	s_mov_b32 m0, s66
	v_lshl_add_u64 v[234:235], s[56:57], 0, v[144:145]
	ds_read_b128 v[200:203], v150 offset:32768
	ds_read_b128 v[204:207], v150 offset:33792
	ds_read_b128 v[208:211], v150 offset:34816
	ds_read_b128 v[212:215], v150 offset:35840
	ds_read_b128 v[216:219], v150 offset:36864
	ds_read_b128 v[220:223], v150 offset:37888
	ds_read_b128 v[224:227], v150 offset:38912
	ds_read_b128 v[228:231], v150 offset:39936
	global_load_lds_dwordx4 v[234:235], off
	v_lshl_add_u64 v[234:235], s[56:57], 0, v[140:141]
	s_mov_b32 m0, s67
	s_nop 0
	global_load_lds_dwordx4 v[234:235], off
	s_waitcnt vmcnt(8)
	s_waitcnt lgkmcnt(0)
	s_barrier
	s_setprio 1
	s_waitcnt lgkmcnt(0)
	v_mfma_f32_16x16x32_bf16 v[124:127], v[152:155], v[200:203], v[124:127]
	v_mfma_f32_16x16x32_bf16 v[120:123], v[160:163], v[200:203], v[120:123]
	v_mfma_f32_16x16x32_bf16 v[112:115], v[152:155], v[208:211], v[112:115]
	v_mfma_f32_16x16x32_bf16 v[104:107], v[160:163], v[208:211], v[104:107]
	v_mfma_f32_16x16x32_bf16 v[96:99], v[152:155], v[216:219], v[96:99]
	v_mfma_f32_16x16x32_bf16 v[88:91], v[160:163], v[216:219], v[88:91]
	v_mfma_f32_16x16x32_bf16 v[80:83], v[152:155], v[224:227], v[80:83]
	v_mfma_f32_16x16x32_bf16 v[72:75], v[160:163], v[224:227], v[72:75]
	v_mfma_f32_16x16x32_bf16 v[124:127], v[156:159], v[204:207], v[124:127]
	v_mfma_f32_16x16x32_bf16 v[120:123], v[164:167], v[204:207], v[120:123]
	v_mfma_f32_16x16x32_bf16 v[112:115], v[156:159], v[212:215], v[112:115]
	v_mfma_f32_16x16x32_bf16 v[104:107], v[164:167], v[212:215], v[104:107]
	v_mfma_f32_16x16x32_bf16 v[96:99], v[156:159], v[220:223], v[96:99]
	v_mfma_f32_16x16x32_bf16 v[88:91], v[164:167], v[220:223], v[88:91]
	v_mfma_f32_16x16x32_bf16 v[80:83], v[156:159], v[228:231], v[80:83]
	v_mfma_f32_16x16x32_bf16 v[72:75], v[164:167], v[228:231], v[72:75]
	v_mfma_f32_16x16x32_bf16 v[116:119], v[184:187], v[200:203], v[116:119]
	v_mfma_f32_16x16x32_bf16 v[108:111], v[192:195], v[200:203], v[108:111]
	v_mfma_f32_16x16x32_bf16 v[100:103], v[184:187], v[208:211], v[100:103]
	v_mfma_f32_16x16x32_bf16 v[92:95], v[192:195], v[208:211], v[92:95]
	v_mfma_f32_16x16x32_bf16 v[84:87], v[184:187], v[216:219], v[84:87]
	v_mfma_f32_16x16x32_bf16 v[76:79], v[192:195], v[216:219], v[76:79]
	v_mfma_f32_16x16x32_bf16 v[68:71], v[184:187], v[224:227], v[68:71]
	v_mfma_f32_16x16x32_bf16 v[64:67], v[192:195], v[224:227], v[64:67]
	v_mfma_f32_16x16x32_bf16 v[116:119], v[188:191], v[204:207], v[116:119]
	v_mfma_f32_16x16x32_bf16 v[108:111], v[196:199], v[204:207], v[108:111]
	v_mfma_f32_16x16x32_bf16 v[100:103], v[188:191], v[212:215], v[100:103]
	v_mfma_f32_16x16x32_bf16 v[92:95], v[196:199], v[212:215], v[92:95]
	v_mfma_f32_16x16x32_bf16 v[84:87], v[188:191], v[220:223], v[84:87]
	v_mfma_f32_16x16x32_bf16 v[76:79], v[196:199], v[220:223], v[76:79]
	v_mfma_f32_16x16x32_bf16 v[68:71], v[188:191], v[228:231], v[68:71]
	v_mfma_f32_16x16x32_bf16 v[64:67], v[196:199], v[228:231], v[64:67]
	s_setprio 0
	s_barrier
; #define PG8_STAGE(bufoff, gbase, voff) do { _Pragma("unroll") for (int _i = 0; _i < 2; ++_i) \
;         __builtin_amdgcn_global_load_lds((const unsigned*)((const char*)(gbase) + (voff)[_i]), (LAS unsigned*)(lds + (bufoff) + ldsw + _i * 8192), 16, 0, 0); } while (0)
; #define PG8_LDA(dst, b, h) do { _Pragma("unroll") for (int m = 0; m < 4; ++m) _Pragma("unroll") for (int k = 0; k < 2; ++k) dst[m][k] = *(const LAS bf16x8*)(lds + PG8_SA(b, h) + aoff + m * 2048 + k * 1024); } while (0)
; #define PG8_MMA(ai, bj, At, Bt) do { __builtin_amdgcn_s_setprio(1); _Pragma("unroll") for (int m = 0; m < 4; ++m) _Pragma("unroll") for (int n = 0; n < 2; ++n) _Pragma("unroll") for (int k = 0; k < 2; ++k) \
;         acc[ai][bj][m][n] = __builtin_amdgcn_mfma_f32_16x16x32_bf16(Bt[n][k], At[m][k], acc[ai][bj][m][n], 0, 0, 0); __builtin_amdgcn_s_setprio(0); } while (0)
; #define PG8_WAIT_V(n) asm volatile("s_waitcnt vmcnt(" #n ")" ::: "memory")
; #define PG8_WAIT_L(n) asm volatile("s_waitcnt lgkmcnt(" #n ")" ::: "memory")
; #define PG8_BAR __builtin_amdgcn_s_barrier()
; #define PG8_SCHED __builtin_amdgcn_sched_barrier(0)
; template <class Epi, class Sched>
; __device__ __forceinline__ void gemm_phase(LAS unsigned char* lds, const int K, const Sched& S, const Epi& E) {
;     ...
;             PG8_LDA(At, 1, 1); PG8_STAGE(PG8_SB(1, 0), b3, voffB); PG8_STAGE(PG8_SB(1, 1), b3 + hstep, voffB); PG8_STAGE(PG8_SA(1, 0), a3, voffA);
;             PG8_WAIT_V(8); PG8_WAIT_L(0); PG8_BAR; PG8_MMA(1, 0, At, B0); PG8_MMA(1, 1, At, B1); PG8_BAR; PG8_SCHED;
;         }
;         if (wr == 0) PG8_BAR;
	s_mov_b32 m0, s12
	v_lshl_add_u64 v[146:147], v[146:147], 0, s[36:37]
	ds_read_b128 v[200:203], v150 offset:49152
	ds_read_b128 v[204:207], v150 offset:50176
	ds_read_b128 v[208:211], v150 offset:51200
	ds_read_b128 v[212:215], v150 offset:52224
	ds_read_b128 v[216:219], v150 offset:53248
	ds_read_b128 v[220:223], v150 offset:54272
	ds_read_b128 v[224:227], v150 offset:55296
	ds_read_b128 v[228:231], v150 offset:56320
	global_load_lds_dwordx4 v[146:147], off
	v_lshl_add_u64 v[146:147], v[180:181], 0, s[36:37]
	s_mov_b32 m0, s11
	s_nop 0
	global_load_lds_dwordx4 v[146:147], off
	v_lshl_add_u64 v[146:147], s[54:55], 0, v[142:143]
	s_mov_b32 m0, s25
	s_nop 0
	global_load_lds_dwordx4 v[146:147], off
	v_lshl_add_u64 v[146:147], s[54:55], 0, v[138:139]
	s_mov_b32 m0, s21
	s_nop 0
	global_load_lds_dwordx4 v[146:147], off
	v_lshl_add_u64 v[146:147], v[182:183], 0, s[36:37]
	s_mov_b32 m0, s0
	s_nop 0
	global_load_lds_dwordx4 v[146:147], off
	v_lshl_add_u64 v[146:147], v[232:233], 0, s[36:37]
	s_mov_b32 m0, s1
	s_nop 0
	global_load_lds_dwordx4 v[146:147], off
	s_waitcnt vmcnt(8)
	s_waitcnt lgkmcnt(0)
	s_barrier
	s_setprio 1
	s_waitcnt lgkmcnt(0)
	v_mfma_f32_16x16x32_bf16 v[60:63], v[152:155], v[200:203], v[60:63]
	v_mfma_f32_16x16x32_bf16 v[56:59], v[160:163], v[200:203], v[56:59]
	v_mfma_f32_16x16x32_bf16 v[48:51], v[152:155], v[208:211], v[48:51]
	v_mfma_f32_16x16x32_bf16 v[40:43], v[160:163], v[208:211], v[40:43]
	v_mfma_f32_16x16x32_bf16 v[32:35], v[152:155], v[216:219], v[32:35]
	v_mfma_f32_16x16x32_bf16 v[24:27], v[160:163], v[216:219], v[24:27]
	v_mfma_f32_16x16x32_bf16 v[16:19], v[152:155], v[224:227], v[16:19]
	v_mfma_f32_16x16x32_bf16 v[8:11], v[160:163], v[224:227], v[8:11]
	v_mfma_f32_16x16x32_bf16 v[60:63], v[156:159], v[204:207], v[60:63]
	v_mfma_f32_16x16x32_bf16 v[56:59], v[164:167], v[204:207], v[56:59]
	v_mfma_f32_16x16x32_bf16 v[48:51], v[156:159], v[212:215], v[48:51]
	v_mfma_f32_16x16x32_bf16 v[40:43], v[164:167], v[212:215], v[40:43]
	v_mfma_f32_16x16x32_bf16 v[32:35], v[156:159], v[220:223], v[32:35]
	v_mfma_f32_16x16x32_bf16 v[24:27], v[164:167], v[220:223], v[24:27]
	v_mfma_f32_16x16x32_bf16 v[16:19], v[156:159], v[228:231], v[16:19]
	v_mfma_f32_16x16x32_bf16 v[8:11], v[164:167], v[228:231], v[8:11]
	v_mfma_f32_16x16x32_bf16 v[52:55], v[184:187], v[200:203], v[52:55]
	v_mfma_f32_16x16x32_bf16 v[44:47], v[192:195], v[200:203], v[44:47]
	v_mfma_f32_16x16x32_bf16 v[36:39], v[184:187], v[208:211], v[36:39]
	v_mfma_f32_16x16x32_bf16 v[28:31], v[192:195], v[208:211], v[28:31]
	v_mfma_f32_16x16x32_bf16 v[20:23], v[184:187], v[216:219], v[20:23]
	v_mfma_f32_16x16x32_bf16 v[12:15], v[192:195], v[216:219], v[12:15]
	v_mfma_f32_16x16x32_bf16 v[4:7], v[184:187], v[224:227], v[4:7]
	v_mfma_f32_16x16x32_bf16 v[0:3], v[192:195], v[224:227], v[0:3]
	v_mfma_f32_16x16x32_bf16 v[52:55], v[188:191], v[204:207], v[52:55]
	v_mfma_f32_16x16x32_bf16 v[44:47], v[196:199], v[204:207], v[44:47]
	v_mfma_f32_16x16x32_bf16 v[36:39], v[188:191], v[212:215], v[36:39]
	v_mfma_f32_16x16x32_bf16 v[28:31], v[196:199], v[212:215], v[28:31]
	v_mfma_f32_16x16x32_bf16 v[20:23], v[188:191], v[220:223], v[20:23]
	v_mfma_f32_16x16x32_bf16 v[12:15], v[196:199], v[220:223], v[12:15]
	v_mfma_f32_16x16x32_bf16 v[4:7], v[188:191], v[228:231], v[4:7]
	v_mfma_f32_16x16x32_bf16 v[0:3], v[196:199], v[228:231], v[0:3]
	s_setprio 0
	s_barrier
	s_movk_i32 s11, 0x100
	s_andn2_b64 vcc, exec, s[52:53]
	s_mov_b64 s[54:55], -1
	s_mov_b64 s[52:53], 0
	s_cbranch_vccz .LBB0_533
	s_and_b64 vcc, exec, s[40:41]
	s_cbranch_vccz .LBB0_536
	s_barrier

; #define PG8_STAGE(bufoff, gbase, voff) do { _Pragma("unroll") for (int _i = 0; _i < 2; ++_i) \
;         __builtin_amdgcn_global_load_lds((const unsigned*)((const char*)(gbase) + (voff)[_i]), (LAS unsigned*)(lds + (bufoff) + ldsw + _i * 8192), 16, 0, 0); } while (0)
; #define PG8_LDA(dst, b, h) do { _Pragma("unroll") for (int m = 0; m < 4; ++m) _Pragma("unroll") for (int k = 0; k < 2; ++k) dst[m][k] = *(const LAS bf16x8*)(lds + PG8_SA(b, h) + aoff + m * 2048 + k * 1024); } while (0)
; #define PG8_LDB(dst, b, h) do { _Pragma("unroll") for (int n = 0; n < 2; ++n) _Pragma("unroll") for (int k = 0; k < 2; ++k) dst[n][k] = *(const LAS bf16x8*)(lds + PG8_SB(b, h) + boff + n * 2048 + k * 1024); } while (0)
; #define PG8_MMA(ai, bj, At, Bt) do { __builtin_amdgcn_s_setprio(1); _Pragma("unroll") for (int m = 0; m < 4; ++m) _Pragma("unroll") for (int n = 0; n < 2; ++n) _Pragma("unroll") for (int k = 0; k < 2; ++k) \
;         acc[ai][bj][m][n] = __builtin_amdgcn_mfma_f32_16x16x32_bf16(Bt[n][k], At[m][k], acc[ai][bj][m][n], 0, 0, 0); __builtin_amdgcn_s_setprio(0); } while (0)
; #define PG8_WAIT_V(n) asm volatile("s_waitcnt vmcnt(" #n ")" ::: "memory")
; #define PG8_WAIT_L(n) asm volatile("s_waitcnt lgkmcnt(" #n ")" ::: "memory")
; #define PG8_BAR __builtin_amdgcn_s_barrier()
; #define PG8_SCHED __builtin_amdgcn_sched_barrier(0)
; template <class Epi, class Sched>
; __device__ __forceinline__ void gemm_phase(LAS unsigned char* lds, const int K, const Sched& S, const Epi& E) {
;     ...
;             const bool last = (t == nt - 2);
;             const char* a1 = cA + (size_t)(t + 1) * kstep;
;             const char* a2 = last ? nA : cA + (size_t)(t + 2) * kstep; const char* b2 = last ? nB : cB + (size_t)(t + 2) * kstep;
;             const char* a3 = a2 + kstep; const char* b3 = b2 + kstep;
;             PG8_LDB(B0, 0, 0); PG8_LDB(B1, 0, 1); PG8_SCHED; PG8_LDA(At, 0, 0); PG8_STAGE(PG8_SA(1, 1), a1 + hstep, voffA);
;             PG8_WAIT_V(8); PG8_WAIT_L(0); PG8_BAR; PG8_MMA(0, 0, At, B0); PG8_MMA(0, 1, At, B1); PG8_BAR; PG8_SCHED;
;             PG8_LDA(At, 0, 1); PG8_STAGE(PG8_SB(0, 0), b2, voffB); PG8_STAGE(PG8_SB(0, 1), b2 + hstep, voffB); PG8_STAGE(PG8_SA(0, 0), a2, voffA);
;             PG8_WAIT_V(8); PG8_WAIT_L(0); PG8_BAR; PG8_MMA(1, 0, At, B0); PG8_MMA(1, 1, At, B1); PG8_BAR; PG8_SCHED;
.LBB0_812:
	s_add_i32 s16, s15, 2
	s_add_u32 s50, s8, 0x100
	s_addc_u32 s51, s9, 0
	s_add_i32 s17, 0, 0x10000
	s_cmp_eq_u32 s12, s15
	s_cselect_b32 s55, s4, s51
	s_cselect_b32 s54, s5, s50
	s_cselect_b32 s53, s10, s14
	s_cselect_b32 s52, s11, s13
	s_add_i32 s15, 0, 0x14000
	v_add_u32_e32 v158, s17, v164
	v_add_u32_e32 v162, s15, v164
	ds_read_b128 v[146:149], v158
	ds_read_b128 v[150:153], v158 offset:1024
	ds_read_b128 v[154:157], v158 offset:2048
	ds_read_b128 v[158:161], v158 offset:3072
	ds_read_b128 v[184:187], v162
	ds_read_b128 v[188:191], v162 offset:1024
	ds_read_b128 v[192:195], v162 offset:2048
	ds_read_b128 v[196:199], v162 offset:3072
	v_lshl_add_u64 v[162:163], s[8:9], 0, v[142:143]
	s_add_i32 m0, s26, 0xc000
	ds_read_b128 v[200:203], v166
	ds_read_b128 v[204:207], v166 offset:1024
	ds_read_b128 v[208:211], v166 offset:2048
	ds_read_b128 v[212:215], v166 offset:3072
	ds_read_b128 v[216:219], v166 offset:4096
	ds_read_b128 v[220:223], v166 offset:5120
	ds_read_b128 v[224:227], v166 offset:6144
	ds_read_b128 v[228:231], v166 offset:7168
	global_load_lds_dwordx4 v[162:163], off
	v_lshl_add_u64 v[162:163], s[8:9], 0, v[144:145]
	s_add_i32 m0, s26, 0xe000
	s_nop 0
	global_load_lds_dwordx4 v[162:163], off
	s_waitcnt vmcnt(8)
	s_waitcnt lgkmcnt(0)
	s_barrier
	s_setprio 1
	s_waitcnt lgkmcnt(0)
	v_mfma_f32_16x16x32_bf16 v[124:127], v[146:149], v[200:203], v[124:127]
	v_mfma_f32_16x16x32_bf16 v[92:95], v[154:157], v[200:203], v[92:95]
	v_mfma_f32_16x16x32_bf16 v[120:123], v[146:149], v[208:211], v[120:123]
	v_mfma_f32_16x16x32_bf16 v[88:91], v[154:157], v[208:211], v[88:91]
	v_mfma_f32_16x16x32_bf16 v[116:119], v[146:149], v[216:219], v[116:119]
	v_mfma_f32_16x16x32_bf16 v[84:87], v[154:157], v[216:219], v[84:87]
	v_mfma_f32_16x16x32_bf16 v[112:115], v[146:149], v[224:227], v[112:115]
	v_mfma_f32_16x16x32_bf16 v[80:83], v[154:157], v[224:227], v[80:83]
	v_mfma_f32_16x16x32_bf16 v[124:127], v[150:153], v[204:207], v[124:127]
	v_mfma_f32_16x16x32_bf16 v[92:95], v[158:161], v[204:207], v[92:95]
	v_mfma_f32_16x16x32_bf16 v[120:123], v[150:153], v[212:215], v[120:123]
	v_mfma_f32_16x16x32_bf16 v[88:91], v[158:161], v[212:215], v[88:91]
	v_mfma_f32_16x16x32_bf16 v[116:119], v[150:153], v[220:223], v[116:119]
	v_mfma_f32_16x16x32_bf16 v[84:87], v[158:161], v[220:223], v[84:87]
	v_mfma_f32_16x16x32_bf16 v[112:115], v[150:153], v[228:231], v[112:115]
	v_mfma_f32_16x16x32_bf16 v[80:83], v[158:161], v[228:231], v[80:83]
	v_mfma_f32_16x16x32_bf16 v[64:67], v[184:187], v[200:203], v[64:67]
	v_mfma_f32_16x16x32_bf16 v[40:43], v[192:195], v[200:203], v[40:43]
	v_mfma_f32_16x16x32_bf16 v[56:59], v[184:187], v[208:211], v[56:59]
	v_mfma_f32_16x16x32_bf16 v[32:35], v[192:195], v[208:211], v[32:35]
	v_mfma_f32_16x16x32_bf16 v[52:55], v[184:187], v[216:219], v[52:55]
	v_mfma_f32_16x16x32_bf16 v[24:27], v[192:195], v[216:219], v[24:27]
	v_mfma_f32_16x16x32_bf16 v[48:51], v[184:187], v[224:227], v[48:51]
	v_mfma_f32_16x16x32_bf16 v[16:19], v[192:195], v[224:227], v[16:19]
	v_mfma_f32_16x16x32_bf16 v[64:67], v[188:191], v[204:207], v[64:67]
	v_mfma_f32_16x16x32_bf16 v[40:43], v[196:199], v[204:207], v[40:43]
	v_mfma_f32_16x16x32_bf16 v[56:59], v[188:191], v[212:215], v[56:59]
	v_mfma_f32_16x16x32_bf16 v[32:35], v[196:199], v[212:215], v[32:35]
	v_mfma_f32_16x16x32_bf16 v[52:55], v[188:191], v[220:223], v[52:55]
	v_mfma_f32_16x16x32_bf16 v[24:27], v[196:199], v[220:223], v[24:27]
	v_mfma_f32_16x16x32_bf16 v[48:51], v[188:191], v[228:231], v[48:51]
	v_mfma_f32_16x16x32_bf16 v[16:19], v[196:199], v[228:231], v[16:19]
	s_setprio 0
	s_barrier
	s_add_i32 s8, s17, s3
	v_lshl_add_u64 v[162:163], s[52:53], 0, v[128:129]
	s_mov_b32 m0, s8
	ds_read_b128 v[200:203], v166 offset:16384
	ds_read_b128 v[204:207], v166 offset:17408
	ds_read_b128 v[208:211], v166 offset:18432
	ds_read_b128 v[212:215], v166 offset:19456
	ds_read_b128 v[216:219], v166 offset:20480
	ds_read_b128 v[220:223], v166 offset:21504
	ds_read_b128 v[224:227], v166 offset:22528
	ds_read_b128 v[228:231], v166 offset:23552
	global_load_lds_dwordx4 v[162:163], off
	s_add_i32 m0, s8, 0x2000
	s_add_u32 s8, s52, 0x50000
	v_lshl_add_u64 v[180:181], s[52:53], 0, v[138:139]
	s_addc_u32 s9, s53, 0
	s_add_i32 s15, s15, s3
	global_load_lds_dwordx4 v[180:181], off
	v_lshl_add_u64 v[182:183], s[8:9], 0, v[128:129]
	s_mov_b32 m0, s15
	v_lshl_add_u64 v[232:233], s[54:55], 0, v[138:139]
	global_load_lds_dwordx4 v[182:183], off
	v_lshl_add_u64 v[182:183], s[8:9], 0, v[138:139]
	s_add_i32 m0, s15, 0x2000
	s_nop 0
	global_load_lds_dwordx4 v[182:183], off
	v_lshl_add_u64 v[182:183], s[54:55], 0, v[128:129]
	s_mov_b32 m0, s26
	s_nop 0
	global_load_lds_dwordx4 v[182:183], off
	s_mov_b32 m0, s27
	s_nop 0
	global_load_lds_dwordx4 v[232:233], off
	s_waitcnt vmcnt(8)
	s_waitcnt lgkmcnt(0)
	s_barrier
; #define PG8_STAGE(bufoff, gbase, voff) do { _Pragma("unroll") for (int _i = 0; _i < 2; ++_i) \
;         __builtin_amdgcn_global_load_lds((const unsigned*)((const char*)(gbase) + (voff)[_i]), (LAS unsigned*)(lds + (bufoff) + ldsw + _i * 8192), 16, 0, 0); } while (0)
; #define PG8_LDA(dst, b, h) do { _Pragma("unroll") for (int m = 0; m < 4; ++m) _Pragma("unroll") for (int k = 0; k < 2; ++k) dst[m][k] = *(const LAS bf16x8*)(lds + PG8_SA(b, h) + aoff + m * 2048 + k * 1024); } while (0)
; #define PG8_LDB(dst, b, h) do { _Pragma("unroll") for (int n = 0; n < 2; ++n) _Pragma("unroll") for (int k = 0; k < 2; ++k) dst[n][k] = *(const LAS bf16x8*)(lds + PG8_SB(b, h) + boff + n * 2048 + k * 1024); } while (0)
; #define PG8_MMA(ai, bj, At, Bt) do { __builtin_amdgcn_s_setprio(1); _Pragma("unroll") for (int m = 0; m < 4; ++m) _Pragma("unroll") for (int n = 0; n < 2; ++n) _Pragma("unroll") for (int k = 0; k < 2; ++k) \
;         acc[ai][bj][m][n] = __builtin_amdgcn_mfma_f32_16x16x32_bf16(Bt[n][k], At[m][k], acc[ai][bj][m][n], 0, 0, 0); __builtin_amdgcn_s_setprio(0); } while (0)
; #define PG8_WAIT_V(n) asm volatile("s_waitcnt vmcnt(" #n ")" ::: "memory")
; #define PG8_WAIT_L(n) asm volatile("s_waitcnt lgkmcnt(" #n ")" ::: "memory")
; #define PG8_BAR __builtin_amdgcn_s_barrier()
; #define PG8_SCHED __builtin_amdgcn_sched_barrier(0)
; template <class Epi, class Sched>
; __device__ __forceinline__ void gemm_phase(LAS unsigned char* lds, const int K, const Sched& S, const Epi& E) {
;     ...
;             PG8_WAIT_V(8); PG8_WAIT_L(0); PG8_BAR; PG8_MMA(1, 0, At, B0); PG8_MMA(1, 1, At, B1); PG8_BAR; PG8_SCHED;
;             PG8_LDB(B0, 1, 0); PG8_LDB(B1, 1, 1); PG8_SCHED; PG8_LDA(At, 1, 0); PG8_STAGE(PG8_SA(0, 1), a2 + hstep, voffA);
;             PG8_WAIT_V(8); PG8_WAIT_L(0); PG8_BAR; PG8_MMA(0, 0, At, B0); PG8_MMA(0, 1, At, B1); PG8_BAR; PG8_SCHED;
	s_setprio 1
	s_waitcnt lgkmcnt(0)
	v_mfma_f32_16x16x32_bf16 v[108:111], v[146:149], v[200:203], v[108:111]
	v_mfma_f32_16x16x32_bf16 v[76:79], v[154:157], v[200:203], v[76:79]
	v_mfma_f32_16x16x32_bf16 v[104:107], v[146:149], v[208:211], v[104:107]
	v_mfma_f32_16x16x32_bf16 v[72:75], v[154:157], v[208:211], v[72:75]
	v_mfma_f32_16x16x32_bf16 v[100:103], v[146:149], v[216:219], v[100:103]
	v_mfma_f32_16x16x32_bf16 v[68:71], v[154:157], v[216:219], v[68:71]
	v_mfma_f32_16x16x32_bf16 v[96:99], v[146:149], v[224:227], v[96:99]
	v_mfma_f32_16x16x32_bf16 v[60:63], v[154:157], v[224:227], v[60:63]
	v_mfma_f32_16x16x32_bf16 v[108:111], v[150:153], v[204:207], v[108:111]
	v_mfma_f32_16x16x32_bf16 v[76:79], v[158:161], v[204:207], v[76:79]
	v_mfma_f32_16x16x32_bf16 v[104:107], v[150:153], v[212:215], v[104:107]
	v_mfma_f32_16x16x32_bf16 v[72:75], v[158:161], v[212:215], v[72:75]
	v_mfma_f32_16x16x32_bf16 v[100:103], v[150:153], v[220:223], v[100:103]
	v_mfma_f32_16x16x32_bf16 v[68:71], v[158:161], v[220:223], v[68:71]
	v_mfma_f32_16x16x32_bf16 v[96:99], v[150:153], v[228:231], v[96:99]
	v_mfma_f32_16x16x32_bf16 v[60:63], v[158:161], v[228:231], v[60:63]
	v_mfma_f32_16x16x32_bf16 v[44:47], v[184:187], v[200:203], v[44:47]
	v_mfma_f32_16x16x32_bf16 v[12:15], v[192:195], v[200:203], v[12:15]
	v_mfma_f32_16x16x32_bf16 v[36:39], v[184:187], v[208:211], v[36:39]
	v_mfma_f32_16x16x32_bf16 v[8:11], v[192:195], v[208:211], v[8:11]
	v_mfma_f32_16x16x32_bf16 v[28:31], v[184:187], v[216:219], v[28:31]
	v_mfma_f32_16x16x32_bf16 v[4:7], v[192:195], v[216:219], v[4:7]
	v_mfma_f32_16x16x32_bf16 v[20:23], v[184:187], v[224:227], v[20:23]
	v_mfma_f32_16x16x32_bf16 v[0:3], v[192:195], v[224:227], v[0:3]
	v_mfma_f32_16x16x32_bf16 v[44:47], v[188:191], v[204:207], v[44:47]
	v_mfma_f32_16x16x32_bf16 v[12:15], v[196:199], v[204:207], v[12:15]
	v_mfma_f32_16x16x32_bf16 v[36:39], v[188:191], v[212:215], v[36:39]
	v_mfma_f32_16x16x32_bf16 v[8:11], v[196:199], v[212:215], v[8:11]
	v_mfma_f32_16x16x32_bf16 v[28:31], v[188:191], v[220:223], v[28:31]
	v_mfma_f32_16x16x32_bf16 v[4:7], v[196:199], v[220:223], v[4:7]
	v_mfma_f32_16x16x32_bf16 v[20:23], v[188:191], v[228:231], v[20:23]
	v_mfma_f32_16x16x32_bf16 v[0:3], v[196:199], v[228:231], v[0:3]
	s_setprio 0
	s_barrier
	s_add_i32 s15, 0, 0x18000
	s_add_i32 s17, 0, 0x1c000
	v_add_u32_e32 v158, s15, v164
	v_add_u32_e32 v167, s17, v164
	ds_read_b128 v[146:149], v158
	ds_read_b128 v[150:153], v158 offset:1024
	ds_read_b128 v[154:157], v158 offset:2048
	ds_read_b128 v[158:161], v158 offset:3072
	ds_read_b128 v[184:187], v167
	ds_read_b128 v[188:191], v167 offset:1024
	ds_read_b128 v[192:195], v167 offset:2048
	ds_read_b128 v[196:199], v167 offset:3072
	s_add_u32 s8, s54, 0x50000
	s_addc_u32 s9, s55, 0
	s_mov_b32 m0, s56
	v_lshl_add_u64 v[234:235], s[8:9], 0, v[128:129]
	ds_read_b128 v[200:203], v166 offset:32768
	ds_read_b128 v[204:207], v166 offset:33792
	ds_read_b128 v[208:211], v166 offset:34816
	ds_read_b128 v[212:215], v166 offset:35840
	ds_read_b128 v[216:219], v166 offset:36864
	ds_read_b128 v[220:223], v166 offset:37888
	ds_read_b128 v[224:227], v166 offset:38912
	ds_read_b128 v[228:231], v166 offset:39936
	global_load_lds_dwordx4 v[234:235], off
	v_lshl_add_u64 v[234:235], s[8:9], 0, v[138:139]
	s_mov_b32 m0, s57
	s_nop 0
	global_load_lds_dwordx4 v[234:235], off
	s_waitcnt vmcnt(8)
	s_waitcnt lgkmcnt(0)
	s_barrier
	s_setprio 1
	s_waitcnt lgkmcnt(0)
	v_mfma_f32_16x16x32_bf16 v[124:127], v[146:149], v[200:203], v[124:127]
	v_mfma_f32_16x16x32_bf16 v[92:95], v[154:157], v[200:203], v[92:95]
	v_mfma_f32_16x16x32_bf16 v[120:123], v[146:149], v[208:211], v[120:123]
	v_mfma_f32_16x16x32_bf16 v[88:91], v[154:157], v[208:211], v[88:91]
	v_mfma_f32_16x16x32_bf16 v[116:119], v[146:149], v[216:219], v[116:119]
	v_mfma_f32_16x16x32_bf16 v[84:87], v[154:157], v[216:219], v[84:87]
	v_mfma_f32_16x16x32_bf16 v[112:115], v[146:149], v[224:227], v[112:115]
	v_mfma_f32_16x16x32_bf16 v[80:83], v[154:157], v[224:227], v[80:83]
	v_mfma_f32_16x16x32_bf16 v[124:127], v[150:153], v[204:207], v[124:127]
	v_mfma_f32_16x16x32_bf16 v[92:95], v[158:161], v[204:207], v[92:95]
	v_mfma_f32_16x16x32_bf16 v[120:123], v[150:153], v[212:215], v[120:123]
	v_mfma_f32_16x16x32_bf16 v[88:91], v[158:161], v[212:215], v[88:91]
	v_mfma_f32_16x16x32_bf16 v[116:119], v[150:153], v[220:223], v[116:119]
	v_mfma_f32_16x16x32_bf16 v[84:87], v[158:161], v[220:223], v[84:87]
	v_mfma_f32_16x16x32_bf16 v[112:115], v[150:153], v[228:231], v[112:115]
	v_mfma_f32_16x16x32_bf16 v[80:83], v[158:161], v[228:231], v[80:83]
	v_mfma_f32_16x16x32_bf16 v[64:67], v[184:187], v[200:203], v[64:67]
	v_mfma_f32_16x16x32_bf16 v[40:43], v[192:195], v[200:203], v[40:43]
	v_mfma_f32_16x16x32_bf16 v[56:59], v[184:187], v[208:211], v[56:59]
	v_mfma_f32_16x16x32_bf16 v[32:35], v[192:195], v[208:211], v[32:35]
	v_mfma_f32_16x16x32_bf16 v[52:55], v[184:187], v[216:219], v[52:55]
	v_mfma_f32_16x16x32_bf16 v[24:27], v[192:195], v[216:219], v[24:27]
	v_mfma_f32_16x16x32_bf16 v[48:51], v[184:187], v[224:227], v[48:51]
	v_mfma_f32_16x16x32_bf16 v[16:19], v[192:195], v[224:227], v[16:19]
	v_mfma_f32_16x16x32_bf16 v[64:67], v[188:191], v[204:207], v[64:67]
	v_mfma_f32_16x16x32_bf16 v[40:43], v[196:199], v[204:207], v[40:43]
	v_mfma_f32_16x16x32_bf16 v[56:59], v[188:191], v[212:215], v[56:59]
	v_mfma_f32_16x16x32_bf16 v[32:35], v[196:199], v[212:215], v[32:35]
	v_mfma_f32_16x16x32_bf16 v[52:55], v[188:191], v[220:223], v[52:55]
	v_mfma_f32_16x16x32_bf16 v[24:27], v[196:199], v[220:223], v[24:27]
	v_mfma_f32_16x16x32_bf16 v[48:51], v[188:191], v[228:231], v[48:51]
	v_mfma_f32_16x16x32_bf16 v[16:19], v[196:199], v[228:231], v[16:19]
	s_setprio 0
	s_barrier
; #define PG8_STAGE(bufoff, gbase, voff) do { _Pragma("unroll") for (int _i = 0; _i < 2; ++_i) \
;         __builtin_amdgcn_global_load_lds((const unsigned*)((const char*)(gbase) + (voff)[_i]), (LAS unsigned*)(lds + (bufoff) + ldsw + _i * 8192), 16, 0, 0); } while (0)
; #define PG8_LDA(dst, b, h) do { _Pragma("unroll") for (int m = 0; m < 4; ++m) _Pragma("unroll") for (int k = 0; k < 2; ++k) dst[m][k] = *(const LAS bf16x8*)(lds + PG8_SA(b, h) + aoff + m * 2048 + k * 1024); } while (0)
; #define PG8_MMA(ai, bj, At, Bt) do { __builtin_amdgcn_s_setprio(1); _Pragma("unroll") for (int m = 0; m < 4; ++m) _Pragma("unroll") for (int n = 0; n < 2; ++n) _Pragma("unroll") for (int k = 0; k < 2; ++k) \
;         acc[ai][bj][m][n] = __builtin_amdgcn_mfma_f32_16x16x32_bf16(Bt[n][k], At[m][k], acc[ai][bj][m][n], 0, 0, 0); __builtin_amdgcn_s_setprio(0); } while (0)
; #define PG8_WAIT_V(n) asm volatile("s_waitcnt vmcnt(" #n ")" ::: "memory")
; #define PG8_WAIT_L(n) asm volatile("s_waitcnt lgkmcnt(" #n ")" ::: "memory")
; #define PG8_BAR __builtin_amdgcn_s_barrier()
; #define PG8_SCHED __builtin_amdgcn_sched_barrier(0)
; template <class Epi, class Sched>
; __device__ __forceinline__ void gemm_phase(LAS unsigned char* lds, const int K, const Sched& S, const Epi& E) {
;     ...
;             PG8_LDA(At, 1, 1); PG8_STAGE(PG8_SB(1, 0), b3, voffB); PG8_STAGE(PG8_SB(1, 1), b3 + hstep, voffB); PG8_STAGE(PG8_SA(1, 0), a3, voffA);
;             PG8_WAIT_V(8); PG8_WAIT_L(0); PG8_BAR; PG8_MMA(1, 0, At, B0); PG8_MMA(1, 1, At, B1); PG8_BAR; PG8_SCHED;
;         }
;         if (wr == 0) PG8_BAR;
	s_add_i32 s8, s15, s3
	v_lshl_add_u64 v[162:163], v[162:163], 0, s[36:37]
	s_mov_b32 m0, s8
	ds_read_b128 v[200:203], v166 offset:49152
	ds_read_b128 v[204:207], v166 offset:50176
	ds_read_b128 v[208:211], v166 offset:51200
	ds_read_b128 v[212:215], v166 offset:52224
	ds_read_b128 v[216:219], v166 offset:53248
	ds_read_b128 v[220:223], v166 offset:54272
	ds_read_b128 v[224:227], v166 offset:55296
	ds_read_b128 v[228:231], v166 offset:56320
	global_load_lds_dwordx4 v[162:163], off
	s_add_i32 m0, s8, 0x2000
	s_add_u32 s8, s52, 0x50080
	v_lshl_add_u64 v[162:163], v[180:181], 0, s[36:37]
	s_addc_u32 s9, s53, 0
	s_add_i32 s15, s17, s3
	global_load_lds_dwordx4 v[162:163], off
	v_lshl_add_u64 v[162:163], s[8:9], 0, v[128:129]
	s_mov_b32 m0, s15
	s_nop 0
	global_load_lds_dwordx4 v[162:163], off
	v_lshl_add_u64 v[162:163], s[8:9], 0, v[138:139]
	s_add_i32 m0, s15, 0x2000
	s_nop 0
	global_load_lds_dwordx4 v[162:163], off
	v_lshl_add_u64 v[162:163], v[182:183], 0, s[36:37]
	s_mov_b32 m0, s58
	s_nop 0
	global_load_lds_dwordx4 v[162:163], off
	v_lshl_add_u64 v[162:163], v[232:233], 0, s[36:37]
	s_mov_b32 m0, s59
	s_nop 0
	global_load_lds_dwordx4 v[162:163], off
	s_waitcnt vmcnt(8)
	s_waitcnt lgkmcnt(0)
	s_barrier
	s_setprio 1
	s_waitcnt lgkmcnt(0)
	v_mfma_f32_16x16x32_bf16 v[108:111], v[146:149], v[200:203], v[108:111]
	v_mfma_f32_16x16x32_bf16 v[76:79], v[154:157], v[200:203], v[76:79]
	v_mfma_f32_16x16x32_bf16 v[104:107], v[146:149], v[208:211], v[104:107]
	v_mfma_f32_16x16x32_bf16 v[72:75], v[154:157], v[208:211], v[72:75]
	v_mfma_f32_16x16x32_bf16 v[100:103], v[146:149], v[216:219], v[100:103]
	v_mfma_f32_16x16x32_bf16 v[68:71], v[154:157], v[216:219], v[68:71]
	v_mfma_f32_16x16x32_bf16 v[96:99], v[146:149], v[224:227], v[96:99]
	v_mfma_f32_16x16x32_bf16 v[60:63], v[154:157], v[224:227], v[60:63]
	v_mfma_f32_16x16x32_bf16 v[108:111], v[150:153], v[204:207], v[108:111]
	v_mfma_f32_16x16x32_bf16 v[76:79], v[158:161], v[204:207], v[76:79]
	v_mfma_f32_16x16x32_bf16 v[104:107], v[150:153], v[212:215], v[104:107]
	v_mfma_f32_16x16x32_bf16 v[72:75], v[158:161], v[212:215], v[72:75]
	v_mfma_f32_16x16x32_bf16 v[100:103], v[150:153], v[220:223], v[100:103]
	v_mfma_f32_16x16x32_bf16 v[68:71], v[158:161], v[220:223], v[68:71]
	v_mfma_f32_16x16x32_bf16 v[96:99], v[150:153], v[228:231], v[96:99]
	v_mfma_f32_16x16x32_bf16 v[60:63], v[158:161], v[228:231], v[60:63]
	v_mfma_f32_16x16x32_bf16 v[44:47], v[184:187], v[200:203], v[44:47]
	v_mfma_f32_16x16x32_bf16 v[12:15], v[192:195], v[200:203], v[12:15]
	v_mfma_f32_16x16x32_bf16 v[36:39], v[184:187], v[208:211], v[36:39]
	v_mfma_f32_16x16x32_bf16 v[8:11], v[192:195], v[208:211], v[8:11]
	v_mfma_f32_16x16x32_bf16 v[28:31], v[184:187], v[216:219], v[28:31]
	v_mfma_f32_16x16x32_bf16 v[4:7], v[192:195], v[216:219], v[4:7]
	v_mfma_f32_16x16x32_bf16 v[20:23], v[184:187], v[224:227], v[20:23]
	v_mfma_f32_16x16x32_bf16 v[0:3], v[192:195], v[224:227], v[0:3]
	v_mfma_f32_16x16x32_bf16 v[44:47], v[188:191], v[204:207], v[44:47]
	v_mfma_f32_16x16x32_bf16 v[12:15], v[196:199], v[204:207], v[12:15]
	v_mfma_f32_16x16x32_bf16 v[36:39], v[188:191], v[212:215], v[36:39]
	v_mfma_f32_16x16x32_bf16 v[8:11], v[196:199], v[212:215], v[8:11]
	v_mfma_f32_16x16x32_bf16 v[28:31], v[188:191], v[220:223], v[28:31]
	v_mfma_f32_16x16x32_bf16 v[4:7], v[196:199], v[220:223], v[4:7]
	v_mfma_f32_16x16x32_bf16 v[20:23], v[188:191], v[228:231], v[20:23]
	v_mfma_f32_16x16x32_bf16 v[0:3], v[196:199], v[228:231], v[0:3]
	s_setprio 0
	s_barrier
	s_add_u32 s13, s13, 0x100
	s_addc_u32 s14, s14, 0
	s_cmp_ge_i32 s16, s2
	s_mov_b64 s[8:9], s[50:51]
	s_mov_b32 s15, s16
	s_cbranch_scc0 .LBB0_812
	s_and_b64 vcc, exec, s[40:41]
	s_cbranch_vccz .LBB0_815
	s_barrier

; #define PG8_STAGE(bufoff, gbase, voff) do { _Pragma("unroll") for (int _i = 0; _i < 2; ++_i) \
;         __builtin_amdgcn_global_load_lds((const unsigned*)((const char*)(gbase) + (voff)[_i]), (LAS unsigned*)(lds + (bufoff) + ldsw + _i * 8192), 16, 0, 0); } while (0)
; #define PG8_LDA(dst, b, h) do { _Pragma("unroll") for (int m = 0; m < 4; ++m) _Pragma("unroll") for (int k = 0; k < 2; ++k) dst[m][k] = *(const LAS bf16x8*)(lds + PG8_SA(b, h) + aoff + m * 2048 + k * 1024); } while (0)
; #define PG8_LDB(dst, b, h) do { _Pragma("unroll") for (int n = 0; n < 2; ++n) _Pragma("unroll") for (int k = 0; k < 2; ++k) dst[n][k] = *(const LAS bf16x8*)(lds + PG8_SB(b, h) + boff + n * 2048 + k * 1024); } while (0)
; #define PG8_MMA(ai, bj, At, Bt) do { __builtin_amdgcn_s_setprio(1); _Pragma("unroll") for (int m = 0; m < 4; ++m) _Pragma("unroll") for (int n = 0; n < 2; ++n) _Pragma("unroll") for (int k = 0; k < 2; ++k) \
;         acc[ai][bj][m][n] = __builtin_amdgcn_mfma_f32_16x16x32_bf16(Bt[n][k], At[m][k], acc[ai][bj][m][n], 0, 0, 0); __builtin_amdgcn_s_setprio(0); } while (0)
; #define PG8_WAIT_V(n) asm volatile("s_waitcnt vmcnt(" #n ")" ::: "memory")
; #define PG8_WAIT_L(n) asm volatile("s_waitcnt lgkmcnt(" #n ")" ::: "memory")
; #define PG8_BAR __builtin_amdgcn_s_barrier()
; #define PG8_SCHED __builtin_amdgcn_sched_barrier(0)
; template <class Epi, class Sched>
; __device__ __forceinline__ void gemm_phase(LAS unsigned char* lds, const int K, const Sched& S, const Epi& E) {
;     ...
;             const bool last = (t == nt - 2);
;             const char* a1 = cA + (size_t)(t + 1) * kstep;
;             const char* a2 = last ? nA : cA + (size_t)(t + 2) * kstep; const char* b2 = last ? nB : cB + (size_t)(t + 2) * kstep;
;             const char* a3 = a2 + kstep; const char* b3 = b2 + kstep;
;             PG8_LDB(B0, 0, 0); PG8_LDB(B1, 0, 1); PG8_SCHED; PG8_LDA(At, 0, 0); PG8_STAGE(PG8_SA(1, 1), a1 + hstep, voffA);
;             PG8_WAIT_V(8); PG8_WAIT_L(0); PG8_BAR; PG8_MMA(0, 0, At, B0); PG8_MMA(0, 1, At, B1); PG8_BAR; PG8_SCHED;
;             PG8_LDA(At, 0, 1); PG8_STAGE(PG8_SB(0, 0), b2, voffB); PG8_STAGE(PG8_SB(0, 1), b2 + hstep, voffB); PG8_STAGE(PG8_SA(0, 0), a2, voffA);
;             PG8_WAIT_V(8); PG8_WAIT_L(0); PG8_BAR; PG8_MMA(1, 0, At, B0); PG8_MMA(1, 1, At, B1); PG8_BAR; PG8_SCHED;
.LBB0_963:
	s_add_u32 s5, s56, 0xfffc0080
	s_addc_u32 s9, s57, -1
	s_add_i32 s10, 0, 0x10000
	s_cmp_eq_u32 s4, 12
	s_cselect_b32 s61, s53, s9
	s_cselect_b32 s60, s52, s5
	v_add_u32_e32 v150, s10, v153
	s_cselect_b32 s59, s55, s2
	s_cselect_b32 s58, s54, s1
	s_add_i32 s5, 0, 0x14000
	ds_read_b128 v[156:159], v150
	ds_read_b128 v[160:163], v150 offset:1024
	ds_read_b128 v[164:167], v150 offset:2048
	ds_read_b128 v[180:183], v150 offset:3072
	v_add_u32_e32 v150, s5, v153
	ds_read_b128 v[184:187], v150
	ds_read_b128 v[188:191], v150 offset:1024
	ds_read_b128 v[192:195], v150 offset:2048
	ds_read_b128 v[196:199], v150 offset:3072
	v_lshl_add_u64 v[150:151], s[56:57], 0, v[146:147]
	s_add_i32 m0, s66, 0xc000
	ds_read_b128 v[200:203], v154
	ds_read_b128 v[204:207], v154 offset:1024
	ds_read_b128 v[208:211], v154 offset:2048
	ds_read_b128 v[212:215], v154 offset:3072
	ds_read_b128 v[216:219], v154 offset:4096
	ds_read_b128 v[220:223], v154 offset:5120
	ds_read_b128 v[224:227], v154 offset:6144
	ds_read_b128 v[228:231], v154 offset:7168
	global_load_lds_dwordx4 v[150:151], off
	v_lshl_add_u64 v[150:151], s[56:57], 0, v[148:149]
	s_add_i32 m0, s66, 0xe000
	s_nop 0
	global_load_lds_dwordx4 v[150:151], off
	s_waitcnt vmcnt(8)
	s_waitcnt lgkmcnt(0)
	s_barrier
	s_setprio 1
	s_waitcnt lgkmcnt(0)
	v_mfma_f32_16x16x32_bf16 v[124:127], v[156:159], v[200:203], v[124:127]
	v_mfma_f32_16x16x32_bf16 v[116:119], v[164:167], v[200:203], v[116:119]
	v_mfma_f32_16x16x32_bf16 v[108:111], v[156:159], v[208:211], v[108:111]
	v_mfma_f32_16x16x32_bf16 v[100:103], v[164:167], v[208:211], v[100:103]
	v_mfma_f32_16x16x32_bf16 v[92:95], v[156:159], v[216:219], v[92:95]
	v_mfma_f32_16x16x32_bf16 v[84:87], v[164:167], v[216:219], v[84:87]
	v_mfma_f32_16x16x32_bf16 v[76:79], v[156:159], v[224:227], v[76:79]
	v_mfma_f32_16x16x32_bf16 v[68:71], v[164:167], v[224:227], v[68:71]
	v_mfma_f32_16x16x32_bf16 v[124:127], v[160:163], v[204:207], v[124:127]
	v_mfma_f32_16x16x32_bf16 v[116:119], v[180:183], v[204:207], v[116:119]
	v_mfma_f32_16x16x32_bf16 v[108:111], v[160:163], v[212:215], v[108:111]
	v_mfma_f32_16x16x32_bf16 v[100:103], v[180:183], v[212:215], v[100:103]
	v_mfma_f32_16x16x32_bf16 v[92:95], v[160:163], v[220:223], v[92:95]
	v_mfma_f32_16x16x32_bf16 v[84:87], v[180:183], v[220:223], v[84:87]
	v_mfma_f32_16x16x32_bf16 v[76:79], v[160:163], v[228:231], v[76:79]
	v_mfma_f32_16x16x32_bf16 v[68:71], v[180:183], v[228:231], v[68:71]
	v_mfma_f32_16x16x32_bf16 v[120:123], v[184:187], v[200:203], v[120:123]
	v_mfma_f32_16x16x32_bf16 v[112:115], v[192:195], v[200:203], v[112:115]
	v_mfma_f32_16x16x32_bf16 v[104:107], v[184:187], v[208:211], v[104:107]
	v_mfma_f32_16x16x32_bf16 v[96:99], v[192:195], v[208:211], v[96:99]
	v_mfma_f32_16x16x32_bf16 v[88:91], v[184:187], v[216:219], v[88:91]
	v_mfma_f32_16x16x32_bf16 v[80:83], v[192:195], v[216:219], v[80:83]
	v_mfma_f32_16x16x32_bf16 v[72:75], v[184:187], v[224:227], v[72:75]
	v_mfma_f32_16x16x32_bf16 v[64:67], v[192:195], v[224:227], v[64:67]
	v_mfma_f32_16x16x32_bf16 v[120:123], v[188:191], v[204:207], v[120:123]
	v_mfma_f32_16x16x32_bf16 v[112:115], v[196:199], v[204:207], v[112:115]
	v_mfma_f32_16x16x32_bf16 v[104:107], v[188:191], v[212:215], v[104:107]
	v_mfma_f32_16x16x32_bf16 v[96:99], v[196:199], v[212:215], v[96:99]
	v_mfma_f32_16x16x32_bf16 v[88:91], v[188:191], v[220:223], v[88:91]
	v_mfma_f32_16x16x32_bf16 v[80:83], v[196:199], v[220:223], v[80:83]
	v_mfma_f32_16x16x32_bf16 v[72:75], v[188:191], v[228:231], v[72:75]
	v_mfma_f32_16x16x32_bf16 v[64:67], v[196:199], v[228:231], v[64:67]
	s_setprio 0
	s_barrier
	s_add_i32 s9, s10, s63
	v_lshl_add_u64 v[150:151], s[58:59], 0, v[142:143]
	s_mov_b32 m0, s9
	ds_read_b128 v[200:203], v154 offset:16384
	ds_read_b128 v[204:207], v154 offset:17408
	ds_read_b128 v[208:211], v154 offset:18432
	ds_read_b128 v[212:215], v154 offset:19456
	ds_read_b128 v[216:219], v154 offset:20480
	ds_read_b128 v[220:223], v154 offset:21504
	ds_read_b128 v[224:227], v154 offset:22528
	ds_read_b128 v[228:231], v154 offset:23552
	global_load_lds_dwordx4 v[150:151], off
	s_add_i32 m0, s9, 0x2000
	s_add_u32 s10, s58, 0x40000
	v_lshl_add_u64 v[232:233], s[58:59], 0, v[138:139]
	s_addc_u32 s11, s59, 0
	s_add_i32 s5, s5, s63
	global_load_lds_dwordx4 v[232:233], off
	v_lshl_add_u64 v[234:235], s[10:11], 0, v[142:143]
	s_mov_b32 m0, s5
	v_lshl_add_u64 v[236:237], s[60:61], 0, v[140:141]
	global_load_lds_dwordx4 v[234:235], off
	v_lshl_add_u64 v[234:235], s[10:11], 0, v[138:139]
	s_add_i32 m0, s5, 0x2000
	s_nop 0
	global_load_lds_dwordx4 v[234:235], off
	v_lshl_add_u64 v[234:235], s[60:61], 0, v[144:145]
	s_mov_b32 m0, s66
	s_nop 0
	global_load_lds_dwordx4 v[234:235], off
	s_mov_b32 m0, s67
	s_nop 0
	global_load_lds_dwordx4 v[236:237], off
	s_waitcnt vmcnt(8)
	s_waitcnt lgkmcnt(0)
	s_barrier
; #define PG8_STAGE(bufoff, gbase, voff) do { _Pragma("unroll") for (int _i = 0; _i < 2; ++_i) \
;         __builtin_amdgcn_global_load_lds((const unsigned*)((const char*)(gbase) + (voff)[_i]), (LAS unsigned*)(lds + (bufoff) + ldsw + _i * 8192), 16, 0, 0); } while (0)
; #define PG8_LDA(dst, b, h) do { _Pragma("unroll") for (int m = 0; m < 4; ++m) _Pragma("unroll") for (int k = 0; k < 2; ++k) dst[m][k] = *(const LAS bf16x8*)(lds + PG8_SA(b, h) + aoff + m * 2048 + k * 1024); } while (0)
; #define PG8_LDB(dst, b, h) do { _Pragma("unroll") for (int n = 0; n < 2; ++n) _Pragma("unroll") for (int k = 0; k < 2; ++k) dst[n][k] = *(const LAS bf16x8*)(lds + PG8_SB(b, h) + boff + n * 2048 + k * 1024); } while (0)
; #define PG8_MMA(ai, bj, At, Bt) do { __builtin_amdgcn_s_setprio(1); _Pragma("unroll") for (int m = 0; m < 4; ++m) _Pragma("unroll") for (int n = 0; n < 2; ++n) _Pragma("unroll") for (int k = 0; k < 2; ++k) \
;         acc[ai][bj][m][n] = __builtin_amdgcn_mfma_f32_16x16x32_bf16(Bt[n][k], At[m][k], acc[ai][bj][m][n], 0, 0, 0); __builtin_amdgcn_s_setprio(0); } while (0)
; #define PG8_WAIT_V(n) asm volatile("s_waitcnt vmcnt(" #n ")" ::: "memory")
; #define PG8_WAIT_L(n) asm volatile("s_waitcnt lgkmcnt(" #n ")" ::: "memory")
; #define PG8_BAR __builtin_amdgcn_s_barrier()
; #define PG8_SCHED __builtin_amdgcn_sched_barrier(0)
; template <class Epi, class Sched>
; __device__ __forceinline__ void gemm_phase(LAS unsigned char* lds, const int K, const Sched& S, const Epi& E) {
;     ...
;             PG8_WAIT_V(8); PG8_WAIT_L(0); PG8_BAR; PG8_MMA(1, 0, At, B0); PG8_MMA(1, 1, At, B1); PG8_BAR; PG8_SCHED;
;             PG8_LDB(B0, 1, 0); PG8_LDB(B1, 1, 1); PG8_SCHED; PG8_LDA(At, 1, 0); PG8_STAGE(PG8_SA(0, 1), a2 + hstep, voffA);
;             PG8_WAIT_V(8); PG8_WAIT_L(0); PG8_BAR; PG8_MMA(0, 0, At, B0); PG8_MMA(0, 1, At, B1); PG8_BAR; PG8_SCHED;
	s_setprio 1
	s_waitcnt lgkmcnt(0)
	v_mfma_f32_16x16x32_bf16 v[60:63], v[156:159], v[200:203], v[60:63]
	v_mfma_f32_16x16x32_bf16 v[52:55], v[164:167], v[200:203], v[52:55]
	v_mfma_f32_16x16x32_bf16 v[44:47], v[156:159], v[208:211], v[44:47]
	v_mfma_f32_16x16x32_bf16 v[36:39], v[164:167], v[208:211], v[36:39]
	v_mfma_f32_16x16x32_bf16 v[28:31], v[156:159], v[216:219], v[28:31]
	v_mfma_f32_16x16x32_bf16 v[20:23], v[164:167], v[216:219], v[20:23]
	v_mfma_f32_16x16x32_bf16 v[12:15], v[156:159], v[224:227], v[12:15]
	v_mfma_f32_16x16x32_bf16 v[4:7], v[164:167], v[224:227], v[4:7]
	v_mfma_f32_16x16x32_bf16 v[60:63], v[160:163], v[204:207], v[60:63]
	v_mfma_f32_16x16x32_bf16 v[52:55], v[180:183], v[204:207], v[52:55]
	v_mfma_f32_16x16x32_bf16 v[44:47], v[160:163], v[212:215], v[44:47]
	v_mfma_f32_16x16x32_bf16 v[36:39], v[180:183], v[212:215], v[36:39]
	v_mfma_f32_16x16x32_bf16 v[28:31], v[160:163], v[220:223], v[28:31]
	v_mfma_f32_16x16x32_bf16 v[20:23], v[180:183], v[220:223], v[20:23]
	v_mfma_f32_16x16x32_bf16 v[12:15], v[160:163], v[228:231], v[12:15]
	v_mfma_f32_16x16x32_bf16 v[4:7], v[180:183], v[228:231], v[4:7]
	v_mfma_f32_16x16x32_bf16 v[56:59], v[184:187], v[200:203], v[56:59]
	v_mfma_f32_16x16x32_bf16 v[48:51], v[192:195], v[200:203], v[48:51]
	v_mfma_f32_16x16x32_bf16 v[40:43], v[184:187], v[208:211], v[40:43]
	v_mfma_f32_16x16x32_bf16 v[32:35], v[192:195], v[208:211], v[32:35]
	v_mfma_f32_16x16x32_bf16 v[24:27], v[184:187], v[216:219], v[24:27]
	v_mfma_f32_16x16x32_bf16 v[16:19], v[192:195], v[216:219], v[16:19]
	v_mfma_f32_16x16x32_bf16 v[8:11], v[184:187], v[224:227], v[8:11]
	v_mfma_f32_16x16x32_bf16 v[0:3], v[192:195], v[224:227], v[0:3]
	v_mfma_f32_16x16x32_bf16 v[56:59], v[188:191], v[204:207], v[56:59]
	v_mfma_f32_16x16x32_bf16 v[48:51], v[196:199], v[204:207], v[48:51]
	v_mfma_f32_16x16x32_bf16 v[40:43], v[188:191], v[212:215], v[40:43]
	v_mfma_f32_16x16x32_bf16 v[32:35], v[196:199], v[212:215], v[32:35]
	v_mfma_f32_16x16x32_bf16 v[24:27], v[188:191], v[220:223], v[24:27]
	v_mfma_f32_16x16x32_bf16 v[16:19], v[196:199], v[220:223], v[16:19]
	v_mfma_f32_16x16x32_bf16 v[8:11], v[188:191], v[228:231], v[8:11]
	v_mfma_f32_16x16x32_bf16 v[0:3], v[196:199], v[228:231], v[0:3]
	s_setprio 0
	s_barrier
	s_add_i32 s5, 0, 0x18000
	v_add_u32_e32 v155, s5, v153
	s_add_i32 s9, 0, 0x1c000
	ds_read_b128 v[156:159], v155
	ds_read_b128 v[160:163], v155 offset:1024
	ds_read_b128 v[164:167], v155 offset:2048
	ds_read_b128 v[180:183], v155 offset:3072
	v_add_u32_e32 v155, s9, v153
	ds_read_b128 v[184:187], v155
	ds_read_b128 v[188:191], v155 offset:1024
	ds_read_b128 v[192:195], v155 offset:2048
	ds_read_b128 v[196:199], v155 offset:3072
	s_add_u32 s10, s60, 0x40000
	s_addc_u32 s11, s61, 0
	s_mov_b32 m0, s68
	v_lshl_add_u64 v[238:239], s[10:11], 0, v[144:145]
	ds_read_b128 v[200:203], v154 offset:32768
	ds_read_b128 v[204:207], v154 offset:33792
	ds_read_b128 v[208:211], v154 offset:34816
	ds_read_b128 v[212:215], v154 offset:35840
	ds_read_b128 v[216:219], v154 offset:36864
	ds_read_b128 v[220:223], v154 offset:37888
	ds_read_b128 v[224:227], v154 offset:38912
	ds_read_b128 v[228:231], v154 offset:39936
	global_load_lds_dwordx4 v[238:239], off
	v_lshl_add_u64 v[238:239], s[10:11], 0, v[140:141]
	s_mov_b32 m0, s69
	s_nop 0
	global_load_lds_dwordx4 v[238:239], off
	s_waitcnt vmcnt(8)
	s_waitcnt lgkmcnt(0)
	s_barrier
	s_setprio 1
	s_waitcnt lgkmcnt(0)
	v_mfma_f32_16x16x32_bf16 v[124:127], v[156:159], v[200:203], v[124:127]
	v_mfma_f32_16x16x32_bf16 v[116:119], v[164:167], v[200:203], v[116:119]
	v_mfma_f32_16x16x32_bf16 v[108:111], v[156:159], v[208:211], v[108:111]
	v_mfma_f32_16x16x32_bf16 v[100:103], v[164:167], v[208:211], v[100:103]
	v_mfma_f32_16x16x32_bf16 v[92:95], v[156:159], v[216:219], v[92:95]
	v_mfma_f32_16x16x32_bf16 v[84:87], v[164:167], v[216:219], v[84:87]
	v_mfma_f32_16x16x32_bf16 v[76:79], v[156:159], v[224:227], v[76:79]
	v_mfma_f32_16x16x32_bf16 v[68:71], v[164:167], v[224:227], v[68:71]
	v_mfma_f32_16x16x32_bf16 v[124:127], v[160:163], v[204:207], v[124:127]
	v_mfma_f32_16x16x32_bf16 v[116:119], v[180:183], v[204:207], v[116:119]
	v_mfma_f32_16x16x32_bf16 v[108:111], v[160:163], v[212:215], v[108:111]
	v_mfma_f32_16x16x32_bf16 v[100:103], v[180:183], v[212:215], v[100:103]
	v_mfma_f32_16x16x32_bf16 v[92:95], v[160:163], v[220:223], v[92:95]
	v_mfma_f32_16x16x32_bf16 v[84:87], v[180:183], v[220:223], v[84:87]
	v_mfma_f32_16x16x32_bf16 v[76:79], v[160:163], v[228:231], v[76:79]
	v_mfma_f32_16x16x32_bf16 v[68:71], v[180:183], v[228:231], v[68:71]
	v_mfma_f32_16x16x32_bf16 v[120:123], v[184:187], v[200:203], v[120:123]
	v_mfma_f32_16x16x32_bf16 v[112:115], v[192:195], v[200:203], v[112:115]
	v_mfma_f32_16x16x32_bf16 v[104:107], v[184:187], v[208:211], v[104:107]
	v_mfma_f32_16x16x32_bf16 v[96:99], v[192:195], v[208:211], v[96:99]
	v_mfma_f32_16x16x32_bf16 v[88:91], v[184:187], v[216:219], v[88:91]
	v_mfma_f32_16x16x32_bf16 v[80:83], v[192:195], v[216:219], v[80:83]
	v_mfma_f32_16x16x32_bf16 v[72:75], v[184:187], v[224:227], v[72:75]
	v_mfma_f32_16x16x32_bf16 v[64:67], v[192:195], v[224:227], v[64:67]
	v_mfma_f32_16x16x32_bf16 v[120:123], v[188:191], v[204:207], v[120:123]
	v_mfma_f32_16x16x32_bf16 v[112:115], v[196:199], v[204:207], v[112:115]
	v_mfma_f32_16x16x32_bf16 v[104:107], v[188:191], v[212:215], v[104:107]
	v_mfma_f32_16x16x32_bf16 v[96:99], v[196:199], v[212:215], v[96:99]
	v_mfma_f32_16x16x32_bf16 v[88:91], v[188:191], v[220:223], v[88:91]
	v_mfma_f32_16x16x32_bf16 v[80:83], v[196:199], v[220:223], v[80:83]
	v_mfma_f32_16x16x32_bf16 v[72:75], v[188:191], v[228:231], v[72:75]
	v_mfma_f32_16x16x32_bf16 v[64:67], v[196:199], v[228:231], v[64:67]
	s_setprio 0
	s_barrier
; #define PG8_STAGE(bufoff, gbase, voff) do { _Pragma("unroll") for (int _i = 0; _i < 2; ++_i) \
;         __builtin_amdgcn_global_load_lds((const unsigned*)((const char*)(gbase) + (voff)[_i]), (LAS unsigned*)(lds + (bufoff) + ldsw + _i * 8192), 16, 0, 0); } while (0)
; #define PG8_LDA(dst, b, h) do { _Pragma("unroll") for (int m = 0; m < 4; ++m) _Pragma("unroll") for (int k = 0; k < 2; ++k) dst[m][k] = *(const LAS bf16x8*)(lds + PG8_SA(b, h) + aoff + m * 2048 + k * 1024); } while (0)
; #define PG8_MMA(ai, bj, At, Bt) do { __builtin_amdgcn_s_setprio(1); _Pragma("unroll") for (int m = 0; m < 4; ++m) _Pragma("unroll") for (int n = 0; n < 2; ++n) _Pragma("unroll") for (int k = 0; k < 2; ++k) \
;         acc[ai][bj][m][n] = __builtin_amdgcn_mfma_f32_16x16x32_bf16(Bt[n][k], At[m][k], acc[ai][bj][m][n], 0, 0, 0); __builtin_amdgcn_s_setprio(0); } while (0)
; #define PG8_WAIT_V(n) asm volatile("s_waitcnt vmcnt(" #n ")" ::: "memory")
; #define PG8_WAIT_L(n) asm volatile("s_waitcnt lgkmcnt(" #n ")" ::: "memory")
; #define PG8_BAR __builtin_amdgcn_s_barrier()
; #define PG8_SCHED __builtin_amdgcn_sched_barrier(0)
; template <class Epi, class Sched>
; __device__ __forceinline__ void gemm_phase(LAS unsigned char* lds, const int K, const Sched& S, const Epi& E) {
;     ...
;             PG8_LDA(At, 1, 1); PG8_STAGE(PG8_SB(1, 0), b3, voffB); PG8_STAGE(PG8_SB(1, 1), b3 + hstep, voffB); PG8_STAGE(PG8_SA(1, 0), a3, voffA);
;             PG8_WAIT_V(8); PG8_WAIT_L(0); PG8_BAR; PG8_MMA(1, 0, At, B0); PG8_MMA(1, 1, At, B1); PG8_BAR; PG8_SCHED;
;         }
;         if (wr == 0) PG8_BAR;
	s_add_i32 s5, s5, s63
	v_lshl_add_u64 v[150:151], v[150:151], 0, s[36:37]
	s_mov_b32 m0, s5
	ds_read_b128 v[200:203], v154 offset:49152
	ds_read_b128 v[204:207], v154 offset:50176
	ds_read_b128 v[208:211], v154 offset:51200
	ds_read_b128 v[212:215], v154 offset:52224
	ds_read_b128 v[216:219], v154 offset:53248
	ds_read_b128 v[220:223], v154 offset:54272
	ds_read_b128 v[224:227], v154 offset:55296
	ds_read_b128 v[228:231], v154 offset:56320
	global_load_lds_dwordx4 v[150:151], off
	s_add_i32 m0, s5, 0x2000
	s_add_u32 s10, s58, 0x40080
	v_lshl_add_u64 v[150:151], v[232:233], 0, s[36:37]
	s_addc_u32 s11, s59, 0
	s_add_i32 s5, s9, s63
	global_load_lds_dwordx4 v[150:151], off
	v_lshl_add_u64 v[150:151], s[10:11], 0, v[142:143]
	s_mov_b32 m0, s5
	s_nop 0
	global_load_lds_dwordx4 v[150:151], off
	v_lshl_add_u64 v[150:151], s[10:11], 0, v[138:139]
	s_add_i32 m0, s5, 0x2000
	s_nop 0
	global_load_lds_dwordx4 v[150:151], off
	v_lshl_add_u64 v[150:151], v[234:235], 0, s[36:37]
	s_mov_b32 m0, s70
	s_nop 0
	global_load_lds_dwordx4 v[150:151], off
	v_lshl_add_u64 v[150:151], v[236:237], 0, s[36:37]
	s_mov_b32 m0, s71
	s_nop 0
	global_load_lds_dwordx4 v[150:151], off
	s_waitcnt vmcnt(8)
	s_waitcnt lgkmcnt(0)
	s_barrier
	s_setprio 1
	s_waitcnt lgkmcnt(0)
	v_mfma_f32_16x16x32_bf16 v[60:63], v[156:159], v[200:203], v[60:63]
	v_mfma_f32_16x16x32_bf16 v[52:55], v[164:167], v[200:203], v[52:55]
	v_mfma_f32_16x16x32_bf16 v[44:47], v[156:159], v[208:211], v[44:47]
	v_mfma_f32_16x16x32_bf16 v[36:39], v[164:167], v[208:211], v[36:39]
	v_mfma_f32_16x16x32_bf16 v[28:31], v[156:159], v[216:219], v[28:31]
	v_mfma_f32_16x16x32_bf16 v[20:23], v[164:167], v[216:219], v[20:23]
	v_mfma_f32_16x16x32_bf16 v[12:15], v[156:159], v[224:227], v[12:15]
	v_mfma_f32_16x16x32_bf16 v[4:7], v[164:167], v[224:227], v[4:7]
	v_mfma_f32_16x16x32_bf16 v[60:63], v[160:163], v[204:207], v[60:63]
	v_mfma_f32_16x16x32_bf16 v[52:55], v[180:183], v[204:207], v[52:55]
	v_mfma_f32_16x16x32_bf16 v[44:47], v[160:163], v[212:215], v[44:47]
	v_mfma_f32_16x16x32_bf16 v[36:39], v[180:183], v[212:215], v[36:39]
	v_mfma_f32_16x16x32_bf16 v[28:31], v[160:163], v[220:223], v[28:31]
	v_mfma_f32_16x16x32_bf16 v[20:23], v[180:183], v[220:223], v[20:23]
	v_mfma_f32_16x16x32_bf16 v[12:15], v[160:163], v[228:231], v[12:15]
	v_mfma_f32_16x16x32_bf16 v[4:7], v[180:183], v[228:231], v[4:7]
	v_mfma_f32_16x16x32_bf16 v[56:59], v[184:187], v[200:203], v[56:59]
	v_mfma_f32_16x16x32_bf16 v[48:51], v[192:195], v[200:203], v[48:51]
	v_mfma_f32_16x16x32_bf16 v[40:43], v[184:187], v[208:211], v[40:43]
	v_mfma_f32_16x16x32_bf16 v[32:35], v[192:195], v[208:211], v[32:35]
	v_mfma_f32_16x16x32_bf16 v[24:27], v[184:187], v[216:219], v[24:27]
	v_mfma_f32_16x16x32_bf16 v[16:19], v[192:195], v[216:219], v[16:19]
	v_mfma_f32_16x16x32_bf16 v[8:11], v[184:187], v[224:227], v[8:11]
	v_mfma_f32_16x16x32_bf16 v[0:3], v[192:195], v[224:227], v[0:3]
	v_mfma_f32_16x16x32_bf16 v[56:59], v[188:191], v[204:207], v[56:59]
	v_mfma_f32_16x16x32_bf16 v[48:51], v[196:199], v[204:207], v[48:51]
	v_mfma_f32_16x16x32_bf16 v[40:43], v[188:191], v[212:215], v[40:43]
	v_mfma_f32_16x16x32_bf16 v[32:35], v[196:199], v[212:215], v[32:35]
	v_mfma_f32_16x16x32_bf16 v[24:27], v[188:191], v[220:223], v[24:27]
	v_mfma_f32_16x16x32_bf16 v[16:19], v[196:199], v[220:223], v[16:19]
	v_mfma_f32_16x16x32_bf16 v[8:11], v[188:191], v[228:231], v[8:11]
	v_mfma_f32_16x16x32_bf16 v[0:3], v[196:199], v[228:231], v[0:3]
	s_setprio 0
	s_barrier
	s_add_i32 s4, s4, 2
	s_add_u32 s56, s56, 0x100
	s_addc_u32 s57, s57, 0
	s_add_u32 s1, s1, 0x100
	s_addc_u32 s2, s2, 0
	s_cmp_gt_u32 s4, 13
	s_cbranch_scc0 .LBB0_963
	s_and_b64 vcc, exec, s[46:47]
	s_cbranch_vccz .LBB0_966
	s_barrier

; #define PG8_STAGE(bufoff, gbase, voff) do { _Pragma("unroll") for (int _i = 0; _i < 2; ++_i) \
;         __builtin_amdgcn_global_load_lds((const unsigned*)((const char*)(gbase) + (voff)[_i]), (LAS unsigned*)(lds + (bufoff) + ldsw + _i * 8192), 16, 0, 0); } while (0)
; #define PG8_LDA(dst, b, h) do { _Pragma("unroll") for (int m = 0; m < 4; ++m) _Pragma("unroll") for (int k = 0; k < 2; ++k) dst[m][k] = *(const LAS bf16x8*)(lds + PG8_SA(b, h) + aoff + m * 2048 + k * 1024); } while (0)
; #define PG8_LDB(dst, b, h) do { _Pragma("unroll") for (int n = 0; n < 2; ++n) _Pragma("unroll") for (int k = 0; k < 2; ++k) dst[n][k] = *(const LAS bf16x8*)(lds + PG8_SB(b, h) + boff + n * 2048 + k * 1024); } while (0)
; #define PG8_MMA(ai, bj, At, Bt) do { __builtin_amdgcn_s_setprio(1); _Pragma("unroll") for (int m = 0; m < 4; ++m) _Pragma("unroll") for (int n = 0; n < 2; ++n) _Pragma("unroll") for (int k = 0; k < 2; ++k) \
;         acc[ai][bj][m][n] = __builtin_amdgcn_mfma_f32_16x16x32_bf16(Bt[n][k], At[m][k], acc[ai][bj][m][n], 0, 0, 0); __builtin_amdgcn_s_setprio(0); } while (0)
; #define PG8_WAIT_V(n) asm volatile("s_waitcnt vmcnt(" #n ")" ::: "memory")
; #define PG8_WAIT_L(n) asm volatile("s_waitcnt lgkmcnt(" #n ")" ::: "memory")
; #define PG8_BAR __builtin_amdgcn_s_barrier()
; #define PG8_SCHED __builtin_amdgcn_sched_barrier(0)
; template <class Epi, class Sched>
; __device__ __forceinline__ void gemm_phase(LAS unsigned char* lds, const int K, const Sched& S, const Epi& E) {
;     ...
;             const bool last = (t == nt - 2);
;             const char* a1 = cA + (size_t)(t + 1) * kstep;
;             const char* a2 = last ? nA : cA + (size_t)(t + 2) * kstep; const char* b2 = last ? nB : cB + (size_t)(t + 2) * kstep;
;             const char* a3 = a2 + kstep; const char* b3 = b2 + kstep;
;             PG8_LDB(B0, 0, 0); PG8_LDB(B1, 0, 1); PG8_SCHED; PG8_LDA(At, 0, 0); PG8_STAGE(PG8_SA(1, 1), a1 + hstep, voffA);
;             PG8_WAIT_V(8); PG8_WAIT_L(0); PG8_BAR; PG8_MMA(0, 0, At, B0); PG8_MMA(0, 1, At, B1); PG8_BAR; PG8_SCHED;
;             PG8_LDA(At, 0, 1); PG8_STAGE(PG8_SB(0, 0), b2, voffB); PG8_STAGE(PG8_SB(0, 1), b2 + hstep, voffB); PG8_STAGE(PG8_SA(0, 0), a2, voffA);
;             PG8_WAIT_V(8); PG8_WAIT_L(0); PG8_BAR; PG8_MMA(1, 0, At, B0); PG8_MMA(1, 1, At, B1); PG8_BAR; PG8_SCHED;
.LBB0_1073:
	s_add_i32 s13, s12, 2
	s_add_u32 s52, s8, 0x100
	s_addc_u32 s53, s9, 0
	s_add_i32 s14, 0, 0x10000
	s_cmp_eq_u32 s5, s12
	s_cselect_b32 s57, s0, s53
	s_cselect_b32 s56, s1, s52
	s_cselect_b32 s55, s2, s11
	s_cselect_b32 s54, s4, s10
	s_add_i32 s12, 0, 0x14000
	v_add_u32_e32 v158, s14, v164
	v_add_u32_e32 v162, s12, v164
	ds_read_b128 v[146:149], v158
	ds_read_b128 v[150:153], v158 offset:1024
	ds_read_b128 v[154:157], v158 offset:2048
	ds_read_b128 v[158:161], v158 offset:3072
	ds_read_b128 v[180:183], v162
	ds_read_b128 v[184:187], v162 offset:1024
	ds_read_b128 v[188:191], v162 offset:2048
	ds_read_b128 v[192:195], v162 offset:3072
	v_lshl_add_u64 v[162:163], s[8:9], 0, v[142:143]
	s_add_i32 m0, s61, 0xc000
	ds_read_b128 v[196:199], v166
	ds_read_b128 v[200:203], v166 offset:1024
	ds_read_b128 v[204:207], v166 offset:2048
	ds_read_b128 v[208:211], v166 offset:3072
	ds_read_b128 v[212:215], v166 offset:4096
	ds_read_b128 v[216:219], v166 offset:5120
	ds_read_b128 v[220:223], v166 offset:6144
	ds_read_b128 v[224:227], v166 offset:7168
	global_load_lds_dwordx4 v[162:163], off
	v_lshl_add_u64 v[162:163], s[8:9], 0, v[144:145]
	s_add_i32 m0, s61, 0xe000
	s_nop 0
	global_load_lds_dwordx4 v[162:163], off
	s_waitcnt vmcnt(8)
	s_waitcnt lgkmcnt(0)
	s_barrier
	s_setprio 1
	s_waitcnt lgkmcnt(0)
	v_mfma_f32_16x16x32_bf16 v[124:127], v[146:149], v[196:199], v[124:127]
	v_mfma_f32_16x16x32_bf16 v[92:95], v[154:157], v[196:199], v[92:95]
	v_mfma_f32_16x16x32_bf16 v[120:123], v[146:149], v[204:207], v[120:123]
	v_mfma_f32_16x16x32_bf16 v[88:91], v[154:157], v[204:207], v[88:91]
	v_mfma_f32_16x16x32_bf16 v[116:119], v[146:149], v[212:215], v[116:119]
	v_mfma_f32_16x16x32_bf16 v[84:87], v[154:157], v[212:215], v[84:87]
	v_mfma_f32_16x16x32_bf16 v[112:115], v[146:149], v[220:223], v[112:115]
	v_mfma_f32_16x16x32_bf16 v[80:83], v[154:157], v[220:223], v[80:83]
	v_mfma_f32_16x16x32_bf16 v[124:127], v[150:153], v[200:203], v[124:127]
	v_mfma_f32_16x16x32_bf16 v[92:95], v[158:161], v[200:203], v[92:95]
	v_mfma_f32_16x16x32_bf16 v[120:123], v[150:153], v[208:211], v[120:123]
	v_mfma_f32_16x16x32_bf16 v[88:91], v[158:161], v[208:211], v[88:91]
	v_mfma_f32_16x16x32_bf16 v[116:119], v[150:153], v[216:219], v[116:119]
	v_mfma_f32_16x16x32_bf16 v[84:87], v[158:161], v[216:219], v[84:87]
	v_mfma_f32_16x16x32_bf16 v[112:115], v[150:153], v[224:227], v[112:115]
	v_mfma_f32_16x16x32_bf16 v[80:83], v[158:161], v[224:227], v[80:83]
	v_mfma_f32_16x16x32_bf16 v[60:63], v[180:183], v[196:199], v[60:63]
	v_mfma_f32_16x16x32_bf16 v[28:31], v[188:191], v[196:199], v[28:31]
	v_mfma_f32_16x16x32_bf16 v[56:59], v[180:183], v[204:207], v[56:59]
	v_mfma_f32_16x16x32_bf16 v[24:27], v[188:191], v[204:207], v[24:27]
	v_mfma_f32_16x16x32_bf16 v[52:55], v[180:183], v[212:215], v[52:55]
	v_mfma_f32_16x16x32_bf16 v[20:23], v[188:191], v[212:215], v[20:23]
	v_mfma_f32_16x16x32_bf16 v[48:51], v[180:183], v[220:223], v[48:51]
	v_mfma_f32_16x16x32_bf16 v[16:19], v[188:191], v[220:223], v[16:19]
	v_mfma_f32_16x16x32_bf16 v[60:63], v[184:187], v[200:203], v[60:63]
	v_mfma_f32_16x16x32_bf16 v[28:31], v[192:195], v[200:203], v[28:31]
	v_mfma_f32_16x16x32_bf16 v[56:59], v[184:187], v[208:211], v[56:59]
	v_mfma_f32_16x16x32_bf16 v[24:27], v[192:195], v[208:211], v[24:27]
	v_mfma_f32_16x16x32_bf16 v[52:55], v[184:187], v[216:219], v[52:55]
	v_mfma_f32_16x16x32_bf16 v[20:23], v[192:195], v[216:219], v[20:23]
	v_mfma_f32_16x16x32_bf16 v[48:51], v[184:187], v[224:227], v[48:51]
	v_mfma_f32_16x16x32_bf16 v[16:19], v[192:195], v[224:227], v[16:19]
	s_setprio 0
	s_barrier
	s_add_i32 s8, s14, s60
	v_lshl_add_u64 v[162:163], s[54:55], 0, v[128:129]
	s_mov_b32 m0, s8
	ds_read_b128 v[196:199], v166 offset:16384
	ds_read_b128 v[200:203], v166 offset:17408
	ds_read_b128 v[204:207], v166 offset:18432
	ds_read_b128 v[208:211], v166 offset:19456
	ds_read_b128 v[212:215], v166 offset:20480
	ds_read_b128 v[216:219], v166 offset:21504
	ds_read_b128 v[220:223], v166 offset:22528
	ds_read_b128 v[224:227], v166 offset:23552
	global_load_lds_dwordx4 v[162:163], off
	s_add_i32 m0, s8, 0x2000
	s_add_u32 s8, s54, 0xb0000
	v_lshl_add_u64 v[228:229], s[54:55], 0, v[138:139]
	s_addc_u32 s9, s55, 0
	s_add_i32 s12, s12, s60
	global_load_lds_dwordx4 v[228:229], off
	v_lshl_add_u64 v[230:231], s[8:9], 0, v[128:129]
	s_mov_b32 m0, s12
	v_lshl_add_u64 v[232:233], s[56:57], 0, v[138:139]
	global_load_lds_dwordx4 v[230:231], off
	v_lshl_add_u64 v[230:231], s[8:9], 0, v[138:139]
	s_add_i32 m0, s12, 0x2000
	s_nop 0
	global_load_lds_dwordx4 v[230:231], off
	v_lshl_add_u64 v[230:231], s[56:57], 0, v[128:129]
	s_mov_b32 m0, s61
	s_nop 0
	global_load_lds_dwordx4 v[230:231], off
	s_mov_b32 m0, s63
	s_nop 0
	global_load_lds_dwordx4 v[232:233], off
	s_waitcnt vmcnt(8)
	s_waitcnt lgkmcnt(0)
	s_barrier
; #define PG8_STAGE(bufoff, gbase, voff) do { _Pragma("unroll") for (int _i = 0; _i < 2; ++_i) \
;         __builtin_amdgcn_global_load_lds((const unsigned*)((const char*)(gbase) + (voff)[_i]), (LAS unsigned*)(lds + (bufoff) + ldsw + _i * 8192), 16, 0, 0); } while (0)
; #define PG8_LDA(dst, b, h) do { _Pragma("unroll") for (int m = 0; m < 4; ++m) _Pragma("unroll") for (int k = 0; k < 2; ++k) dst[m][k] = *(const LAS bf16x8*)(lds + PG8_SA(b, h) + aoff + m * 2048 + k * 1024); } while (0)
; #define PG8_LDB(dst, b, h) do { _Pragma("unroll") for (int n = 0; n < 2; ++n) _Pragma("unroll") for (int k = 0; k < 2; ++k) dst[n][k] = *(const LAS bf16x8*)(lds + PG8_SB(b, h) + boff + n * 2048 + k * 1024); } while (0)
; #define PG8_MMA(ai, bj, At, Bt) do { __builtin_amdgcn_s_setprio(1); _Pragma("unroll") for (int m = 0; m < 4; ++m) _Pragma("unroll") for (int n = 0; n < 2; ++n) _Pragma("unroll") for (int k = 0; k < 2; ++k) \
;         acc[ai][bj][m][n] = __builtin_amdgcn_mfma_f32_16x16x32_bf16(Bt[n][k], At[m][k], acc[ai][bj][m][n], 0, 0, 0); __builtin_amdgcn_s_setprio(0); } while (0)
; #define PG8_WAIT_V(n) asm volatile("s_waitcnt vmcnt(" #n ")" ::: "memory")
; #define PG8_WAIT_L(n) asm volatile("s_waitcnt lgkmcnt(" #n ")" ::: "memory")
; #define PG8_BAR __builtin_amdgcn_s_barrier()
; #define PG8_SCHED __builtin_amdgcn_sched_barrier(0)
; template <class Epi, class Sched>
; __device__ __forceinline__ void gemm_phase(LAS unsigned char* lds, const int K, const Sched& S, const Epi& E) {
;     ...
;             PG8_WAIT_V(8); PG8_WAIT_L(0); PG8_BAR; PG8_MMA(1, 0, At, B0); PG8_MMA(1, 1, At, B1); PG8_BAR; PG8_SCHED;
;             PG8_LDB(B0, 1, 0); PG8_LDB(B1, 1, 1); PG8_SCHED; PG8_LDA(At, 1, 0); PG8_STAGE(PG8_SA(0, 1), a2 + hstep, voffA);
;             PG8_WAIT_V(8); PG8_WAIT_L(0); PG8_BAR; PG8_MMA(0, 0, At, B0); PG8_MMA(0, 1, At, B1); PG8_BAR; PG8_SCHED;
	s_setprio 1
	s_waitcnt lgkmcnt(0)
	v_mfma_f32_16x16x32_bf16 v[108:111], v[146:149], v[196:199], v[108:111]
	v_mfma_f32_16x16x32_bf16 v[76:79], v[154:157], v[196:199], v[76:79]
	v_mfma_f32_16x16x32_bf16 v[104:107], v[146:149], v[204:207], v[104:107]
	v_mfma_f32_16x16x32_bf16 v[72:75], v[154:157], v[204:207], v[72:75]
	v_mfma_f32_16x16x32_bf16 v[100:103], v[146:149], v[212:215], v[100:103]
	v_mfma_f32_16x16x32_bf16 v[68:71], v[154:157], v[212:215], v[68:71]
	v_mfma_f32_16x16x32_bf16 v[96:99], v[146:149], v[220:223], v[96:99]
	v_mfma_f32_16x16x32_bf16 v[64:67], v[154:157], v[220:223], v[64:67]
	v_mfma_f32_16x16x32_bf16 v[108:111], v[150:153], v[200:203], v[108:111]
	v_mfma_f32_16x16x32_bf16 v[76:79], v[158:161], v[200:203], v[76:79]
	v_mfma_f32_16x16x32_bf16 v[104:107], v[150:153], v[208:211], v[104:107]
	v_mfma_f32_16x16x32_bf16 v[72:75], v[158:161], v[208:211], v[72:75]
	v_mfma_f32_16x16x32_bf16 v[100:103], v[150:153], v[216:219], v[100:103]
	v_mfma_f32_16x16x32_bf16 v[68:71], v[158:161], v[216:219], v[68:71]
	v_mfma_f32_16x16x32_bf16 v[96:99], v[150:153], v[224:227], v[96:99]
	v_mfma_f32_16x16x32_bf16 v[64:67], v[158:161], v[224:227], v[64:67]
	v_mfma_f32_16x16x32_bf16 v[44:47], v[180:183], v[196:199], v[44:47]
	v_mfma_f32_16x16x32_bf16 v[12:15], v[188:191], v[196:199], v[12:15]
	v_mfma_f32_16x16x32_bf16 v[40:43], v[180:183], v[204:207], v[40:43]
	v_mfma_f32_16x16x32_bf16 v[8:11], v[188:191], v[204:207], v[8:11]
	v_mfma_f32_16x16x32_bf16 v[36:39], v[180:183], v[212:215], v[36:39]
	v_mfma_f32_16x16x32_bf16 v[4:7], v[188:191], v[212:215], v[4:7]
	v_mfma_f32_16x16x32_bf16 v[32:35], v[180:183], v[220:223], v[32:35]
	v_mfma_f32_16x16x32_bf16 v[0:3], v[188:191], v[220:223], v[0:3]
	v_mfma_f32_16x16x32_bf16 v[44:47], v[184:187], v[200:203], v[44:47]
	v_mfma_f32_16x16x32_bf16 v[12:15], v[192:195], v[200:203], v[12:15]
	v_mfma_f32_16x16x32_bf16 v[40:43], v[184:187], v[208:211], v[40:43]
	v_mfma_f32_16x16x32_bf16 v[8:11], v[192:195], v[208:211], v[8:11]
	v_mfma_f32_16x16x32_bf16 v[36:39], v[184:187], v[216:219], v[36:39]
	v_mfma_f32_16x16x32_bf16 v[4:7], v[192:195], v[216:219], v[4:7]
	v_mfma_f32_16x16x32_bf16 v[32:35], v[184:187], v[224:227], v[32:35]
	v_mfma_f32_16x16x32_bf16 v[0:3], v[192:195], v[224:227], v[0:3]
	s_setprio 0
	s_barrier
	s_add_i32 s12, 0, 0x18000
	s_add_i32 s14, 0, 0x1c000
	v_add_u32_e32 v158, s12, v164
	v_add_u32_e32 v167, s14, v164
	ds_read_b128 v[146:149], v158
	ds_read_b128 v[150:153], v158 offset:1024
	ds_read_b128 v[154:157], v158 offset:2048
	ds_read_b128 v[158:161], v158 offset:3072
	ds_read_b128 v[180:183], v167
	ds_read_b128 v[184:187], v167 offset:1024
	ds_read_b128 v[188:191], v167 offset:2048
	ds_read_b128 v[192:195], v167 offset:3072
	s_add_u32 s8, s56, 0xb0000
	s_addc_u32 s9, s57, 0
	s_mov_b32 m0, s64
	v_lshl_add_u64 v[234:235], s[8:9], 0, v[128:129]
	ds_read_b128 v[196:199], v166 offset:32768
	ds_read_b128 v[200:203], v166 offset:33792
	ds_read_b128 v[204:207], v166 offset:34816
	ds_read_b128 v[208:211], v166 offset:35840
	ds_read_b128 v[212:215], v166 offset:36864
	ds_read_b128 v[216:219], v166 offset:37888
	ds_read_b128 v[220:223], v166 offset:38912
	ds_read_b128 v[224:227], v166 offset:39936
	global_load_lds_dwordx4 v[234:235], off
	v_lshl_add_u64 v[234:235], s[8:9], 0, v[138:139]
	s_mov_b32 m0, s65
	s_nop 0
	global_load_lds_dwordx4 v[234:235], off
	s_waitcnt vmcnt(8)
	s_waitcnt lgkmcnt(0)
	s_barrier
	s_setprio 1
	s_waitcnt lgkmcnt(0)
	v_mfma_f32_16x16x32_bf16 v[124:127], v[146:149], v[196:199], v[124:127]
	v_mfma_f32_16x16x32_bf16 v[92:95], v[154:157], v[196:199], v[92:95]
	v_mfma_f32_16x16x32_bf16 v[120:123], v[146:149], v[204:207], v[120:123]
	v_mfma_f32_16x16x32_bf16 v[88:91], v[154:157], v[204:207], v[88:91]
	v_mfma_f32_16x16x32_bf16 v[116:119], v[146:149], v[212:215], v[116:119]
	v_mfma_f32_16x16x32_bf16 v[84:87], v[154:157], v[212:215], v[84:87]
	v_mfma_f32_16x16x32_bf16 v[112:115], v[146:149], v[220:223], v[112:115]
	v_mfma_f32_16x16x32_bf16 v[80:83], v[154:157], v[220:223], v[80:83]
	v_mfma_f32_16x16x32_bf16 v[124:127], v[150:153], v[200:203], v[124:127]
	v_mfma_f32_16x16x32_bf16 v[92:95], v[158:161], v[200:203], v[92:95]
	v_mfma_f32_16x16x32_bf16 v[120:123], v[150:153], v[208:211], v[120:123]
	v_mfma_f32_16x16x32_bf16 v[88:91], v[158:161], v[208:211], v[88:91]
	v_mfma_f32_16x16x32_bf16 v[116:119], v[150:153], v[216:219], v[116:119]
	v_mfma_f32_16x16x32_bf16 v[84:87], v[158:161], v[216:219], v[84:87]
	v_mfma_f32_16x16x32_bf16 v[112:115], v[150:153], v[224:227], v[112:115]
	v_mfma_f32_16x16x32_bf16 v[80:83], v[158:161], v[224:227], v[80:83]
	v_mfma_f32_16x16x32_bf16 v[60:63], v[180:183], v[196:199], v[60:63]
	v_mfma_f32_16x16x32_bf16 v[28:31], v[188:191], v[196:199], v[28:31]
	v_mfma_f32_16x16x32_bf16 v[56:59], v[180:183], v[204:207], v[56:59]
	v_mfma_f32_16x16x32_bf16 v[24:27], v[188:191], v[204:207], v[24:27]
	v_mfma_f32_16x16x32_bf16 v[52:55], v[180:183], v[212:215], v[52:55]
	v_mfma_f32_16x16x32_bf16 v[20:23], v[188:191], v[212:215], v[20:23]
	v_mfma_f32_16x16x32_bf16 v[48:51], v[180:183], v[220:223], v[48:51]
	v_mfma_f32_16x16x32_bf16 v[16:19], v[188:191], v[220:223], v[16:19]
	v_mfma_f32_16x16x32_bf16 v[60:63], v[184:187], v[200:203], v[60:63]
	v_mfma_f32_16x16x32_bf16 v[28:31], v[192:195], v[200:203], v[28:31]
	v_mfma_f32_16x16x32_bf16 v[56:59], v[184:187], v[208:211], v[56:59]
	v_mfma_f32_16x16x32_bf16 v[24:27], v[192:195], v[208:211], v[24:27]
	v_mfma_f32_16x16x32_bf16 v[52:55], v[184:187], v[216:219], v[52:55]
	v_mfma_f32_16x16x32_bf16 v[20:23], v[192:195], v[216:219], v[20:23]
	v_mfma_f32_16x16x32_bf16 v[48:51], v[184:187], v[224:227], v[48:51]
	v_mfma_f32_16x16x32_bf16 v[16:19], v[192:195], v[224:227], v[16:19]
	s_setprio 0
	s_barrier
; #define PG8_STAGE(bufoff, gbase, voff) do { _Pragma("unroll") for (int _i = 0; _i < 2; ++_i) \
;         __builtin_amdgcn_global_load_lds((const unsigned*)((const char*)(gbase) + (voff)[_i]), (LAS unsigned*)(lds + (bufoff) + ldsw + _i * 8192), 16, 0, 0); } while (0)
; #define PG8_LDA(dst, b, h) do { _Pragma("unroll") for (int m = 0; m < 4; ++m) _Pragma("unroll") for (int k = 0; k < 2; ++k) dst[m][k] = *(const LAS bf16x8*)(lds + PG8_SA(b, h) + aoff + m * 2048 + k * 1024); } while (0)
; #define PG8_MMA(ai, bj, At, Bt) do { __builtin_amdgcn_s_setprio(1); _Pragma("unroll") for (int m = 0; m < 4; ++m) _Pragma("unroll") for (int n = 0; n < 2; ++n) _Pragma("unroll") for (int k = 0; k < 2; ++k) \
;         acc[ai][bj][m][n] = __builtin_amdgcn_mfma_f32_16x16x32_bf16(Bt[n][k], At[m][k], acc[ai][bj][m][n], 0, 0, 0); __builtin_amdgcn_s_setprio(0); } while (0)
; #define PG8_WAIT_V(n) asm volatile("s_waitcnt vmcnt(" #n ")" ::: "memory")
; #define PG8_WAIT_L(n) asm volatile("s_waitcnt lgkmcnt(" #n ")" ::: "memory")
; #define PG8_BAR __builtin_amdgcn_s_barrier()
; #define PG8_SCHED __builtin_amdgcn_sched_barrier(0)
; template <class Epi, class Sched>
; __device__ __forceinline__ void gemm_phase(LAS unsigned char* lds, const int K, const Sched& S, const Epi& E) {
;     ...
;             PG8_LDA(At, 1, 1); PG8_STAGE(PG8_SB(1, 0), b3, voffB); PG8_STAGE(PG8_SB(1, 1), b3 + hstep, voffB); PG8_STAGE(PG8_SA(1, 0), a3, voffA);
;             PG8_WAIT_V(8); PG8_WAIT_L(0); PG8_BAR; PG8_MMA(1, 0, At, B0); PG8_MMA(1, 1, At, B1); PG8_BAR; PG8_SCHED;
;         }
;         if (wr == 0) PG8_BAR;
	s_add_i32 s8, s12, s60
	v_lshl_add_u64 v[162:163], v[162:163], 0, s[36:37]
	s_mov_b32 m0, s8
	ds_read_b128 v[196:199], v166 offset:49152
	ds_read_b128 v[200:203], v166 offset:50176
	ds_read_b128 v[204:207], v166 offset:51200
	ds_read_b128 v[208:211], v166 offset:52224
	ds_read_b128 v[212:215], v166 offset:53248
	ds_read_b128 v[216:219], v166 offset:54272
	ds_read_b128 v[220:223], v166 offset:55296
	ds_read_b128 v[224:227], v166 offset:56320
	global_load_lds_dwordx4 v[162:163], off
	s_add_i32 m0, s8, 0x2000
	s_add_u32 s8, s54, 0xb0080
	v_lshl_add_u64 v[162:163], v[228:229], 0, s[36:37]
	s_addc_u32 s9, s55, 0
	s_add_i32 s12, s14, s60
	global_load_lds_dwordx4 v[162:163], off
	v_lshl_add_u64 v[162:163], s[8:9], 0, v[128:129]
	s_mov_b32 m0, s12
	s_nop 0
	global_load_lds_dwordx4 v[162:163], off
	v_lshl_add_u64 v[162:163], s[8:9], 0, v[138:139]
	s_add_i32 m0, s12, 0x2000
	s_nop 0
	global_load_lds_dwordx4 v[162:163], off
	v_lshl_add_u64 v[162:163], v[230:231], 0, s[36:37]
	s_mov_b32 m0, s68
	s_nop 0
	global_load_lds_dwordx4 v[162:163], off
	v_lshl_add_u64 v[162:163], v[232:233], 0, s[36:37]
	s_mov_b32 m0, s69
	s_nop 0
	global_load_lds_dwordx4 v[162:163], off
	s_waitcnt vmcnt(8)
	s_waitcnt lgkmcnt(0)
	s_barrier
	s_setprio 1
	s_waitcnt lgkmcnt(0)
	v_mfma_f32_16x16x32_bf16 v[108:111], v[146:149], v[196:199], v[108:111]
	v_mfma_f32_16x16x32_bf16 v[76:79], v[154:157], v[196:199], v[76:79]
	v_mfma_f32_16x16x32_bf16 v[104:107], v[146:149], v[204:207], v[104:107]
	v_mfma_f32_16x16x32_bf16 v[72:75], v[154:157], v[204:207], v[72:75]
	v_mfma_f32_16x16x32_bf16 v[100:103], v[146:149], v[212:215], v[100:103]
	v_mfma_f32_16x16x32_bf16 v[68:71], v[154:157], v[212:215], v[68:71]
	v_mfma_f32_16x16x32_bf16 v[96:99], v[146:149], v[220:223], v[96:99]
	v_mfma_f32_16x16x32_bf16 v[64:67], v[154:157], v[220:223], v[64:67]
	v_mfma_f32_16x16x32_bf16 v[108:111], v[150:153], v[200:203], v[108:111]
	v_mfma_f32_16x16x32_bf16 v[76:79], v[158:161], v[200:203], v[76:79]
	v_mfma_f32_16x16x32_bf16 v[104:107], v[150:153], v[208:211], v[104:107]
	v_mfma_f32_16x16x32_bf16 v[72:75], v[158:161], v[208:211], v[72:75]
	v_mfma_f32_16x16x32_bf16 v[100:103], v[150:153], v[216:219], v[100:103]
	v_mfma_f32_16x16x32_bf16 v[68:71], v[158:161], v[216:219], v[68:71]
	v_mfma_f32_16x16x32_bf16 v[96:99], v[150:153], v[224:227], v[96:99]
	v_mfma_f32_16x16x32_bf16 v[64:67], v[158:161], v[224:227], v[64:67]
	v_mfma_f32_16x16x32_bf16 v[44:47], v[180:183], v[196:199], v[44:47]
	v_mfma_f32_16x16x32_bf16 v[12:15], v[188:191], v[196:199], v[12:15]
	v_mfma_f32_16x16x32_bf16 v[40:43], v[180:183], v[204:207], v[40:43]
	v_mfma_f32_16x16x32_bf16 v[8:11], v[188:191], v[204:207], v[8:11]
	v_mfma_f32_16x16x32_bf16 v[36:39], v[180:183], v[212:215], v[36:39]
	v_mfma_f32_16x16x32_bf16 v[4:7], v[188:191], v[212:215], v[4:7]
	v_mfma_f32_16x16x32_bf16 v[32:35], v[180:183], v[220:223], v[32:35]
	v_mfma_f32_16x16x32_bf16 v[0:3], v[188:191], v[220:223], v[0:3]
	v_mfma_f32_16x16x32_bf16 v[44:47], v[184:187], v[200:203], v[44:47]
	v_mfma_f32_16x16x32_bf16 v[12:15], v[192:195], v[200:203], v[12:15]
	v_mfma_f32_16x16x32_bf16 v[40:43], v[184:187], v[208:211], v[40:43]
	v_mfma_f32_16x16x32_bf16 v[8:11], v[192:195], v[208:211], v[8:11]
	v_mfma_f32_16x16x32_bf16 v[36:39], v[184:187], v[216:219], v[36:39]
	v_mfma_f32_16x16x32_bf16 v[4:7], v[192:195], v[216:219], v[4:7]
	v_mfma_f32_16x16x32_bf16 v[32:35], v[184:187], v[224:227], v[32:35]
	v_mfma_f32_16x16x32_bf16 v[0:3], v[192:195], v[224:227], v[0:3]
	s_setprio 0
	s_barrier
	s_add_u32 s10, s10, 0x100
	s_addc_u32 s11, s11, 0
	s_cmp_ge_i32 s13, s51
	s_mov_b64 s[8:9], s[52:53]
	s_mov_b32 s12, s13
	s_cbranch_scc0 .LBB0_1073
	s_and_b64 vcc, exec, s[40:41]
	s_cbranch_vccz .LBB0_1076
